# LN/norm/expert-tail wave sums as DPP + permlane swaps instead of ds_bpermute round trips
# speedup vs baseline: 1.0208x; 1.0097x over previous
; __device__ __forceinline__ unsigned pk2(float lo, float hi) { return f2bf(lo) | (f2bf(hi) << 16); }
; __device__ __forceinline__ void phase_expert(CArgs& A, int l, unsigned char* lds, int tid, bool dry = false) {
;     ...
;         for (int i = 0; i < 8; ++i) { s[2 * i] = ff[i].x + ALPHA * x[i].x; s[2 * i + 1] = ff[i].y + ALPHA * x[i].y; }
; #pragma unroll
;         for (int i = 0; i < 4; ++i) { const f32x4 a = *(const f32x4*)(lg + lane * 4 + 256 * i), b4 = *(const f32x4*)(lb + lane * 4 + 256 * i);
;             gg[4 * i] = a.x; gg[4 * i + 1] = a.y; gg[4 * i + 2] = a.z; gg[4 * i + 3] = a.w; bv[4 * i] = b4.x; bv[4 * i + 1] = b4.y; bv[4 * i + 2] = b4.z; bv[4 * i + 3] = b4.w; }
;         float sum = 0.f;
; #pragma unroll
;         for (int i = 0; i < 16; ++i) sum += s[i];
;         const float mean = wave_sum(sum) * (1.f / DM);
;         float qq = 0.f;
; #pragma unroll
;         for (int i = 0; i < 16; ++i) { s[i] -= mean; qq += s[i] * s[i]; }
;         const float rstd = rsqrtf(wave_sum(qq) * (1.f / DM) + LN_EPS);
; #pragma unroll
;         for (int i = 0; i < 16; ++i) s[i] = s[i] * rstd * gg[i] + bv[i];
;         if (dry) { if (s[0] == 12345.678f) X[(size_t)t * DM + lane * 16] = 0; continue; }
;         { bf16* xr = X + (size_t)t * DM + lane * 4;
; #pragma unroll
;           for (int i = 0; i < 4; ++i) { u32x2 w; w.x = pk2(s[4 * i], s[4 * i + 1]); w.y = pk2(s[4 * i + 2], s[4 * i + 3]); *(u32x2*)(xr + 256 * i) = w; } }
.Lpx_done:
.LBB0_117:
	s_mov_b32 s0, 0x3fb504f3
	v_pk_fma_f32 v[34:35], v[156:157], s[0:1], v[158:159] op_sel_hi:[1,0,1]
	v_pk_fma_f32 v[48:49], v[144:145], s[0:1], v[248:249] op_sel_hi:[1,0,1]
	v_add_f32_e32 v36, 0, v34
	v_add_f32_e32 v38, v35, v36
	v_pk_fma_f32 v[36:37], v[154:155], s[0:1], v[160:161] op_sel_hi:[1,0,1]
	v_pk_fma_f32 v[44:45], v[140:141], s[0:1], v[124:125] op_sel_hi:[1,0,1]
	v_add_f32_e32 v38, v36, v38
	v_add_f32_e32 v40, v37, v38
	v_pk_fma_f32 v[38:39], v[152:153], s[0:1], v[240:241] op_sel_hi:[1,0,1]
	s_mov_b64 s[4:5], -1
	v_add_f32_e32 v40, v38, v40
	v_add_f32_e32 v42, v39, v40
	v_pk_fma_f32 v[40:41], v[150:151], s[0:1], v[242:243] op_sel_hi:[1,0,1]
	s_nop 0
	v_add_f32_e32 v42, v40, v42
	v_add_f32_e32 v46, v41, v42
	v_pk_fma_f32 v[42:43], v[148:149], s[0:1], v[244:245] op_sel_hi:[1,0,1]
	s_nop 0
	v_add_f32_e32 v46, v42, v46
	v_add_f32_e32 v50, v43, v46
	v_pk_fma_f32 v[46:47], v[146:147], s[0:1], v[246:247] op_sel_hi:[1,0,1]
	s_mov_b32 s0, 0x800000
	v_add_f32_e32 v50, v46, v50
	v_add_f32_e32 v50, v47, v50
	v_add_f32_e32 v50, v48, v50
	v_add_f32_e32 v50, v49, v50
	v_add_f32_e32 v50, v44, v50
	v_add_f32_e32 v50, v45, v50
	s_waitcnt lgkmcnt(0)
	s_nop 1
	v_add_f32_dpp v50, v50, v50 quad_perm:[1,0,3,2] row_mask:0xf bank_mask:0xf
	s_waitcnt lgkmcnt(0)
	s_nop 1
	v_add_f32_dpp v50, v50, v50 quad_perm:[2,3,0,1] row_mask:0xf bank_mask:0xf
	s_waitcnt lgkmcnt(0)
	s_nop 1
	v_add_f32_dpp v50, v50, v50 row_half_mirror row_mask:0xf bank_mask:0xf
	s_waitcnt lgkmcnt(0)
	s_nop 1
	v_add_f32_dpp v50, v50, v50 row_mirror row_mask:0xf bank_mask:0xf
	s_waitcnt lgkmcnt(0)
	v_mov_b32_e32 v51, v50
	s_nop 1
	v_permlane16_swap_b32_e32 v50, v51
	v_add_f32_e32 v50, v50, v51
	s_waitcnt lgkmcnt(0)
	v_mov_b32_e32 v51, v50
	s_nop 1
	v_permlane32_swap_b32_e32 v50, v51
	v_add_f32_e32 v50, v50, v51
	v_mul_f32_e32 v50, 0x3a800000, v50
	v_pk_add_f32 v[34:35], v[34:35], v[50:51] op_sel_hi:[1,0] neg_lo:[0,1] neg_hi:[0,1]
	v_pk_add_f32 v[36:37], v[36:37], v[50:51] op_sel_hi:[1,0] neg_lo:[0,1] neg_hi:[0,1]
	v_pk_add_f32 v[38:39], v[38:39], v[50:51] op_sel_hi:[1,0] neg_lo:[0,1] neg_hi:[0,1]
	v_pk_add_f32 v[40:41], v[40:41], v[50:51] op_sel_hi:[1,0] neg_lo:[0,1] neg_hi:[0,1]
	v_pk_add_f32 v[42:43], v[42:43], v[50:51] op_sel_hi:[1,0] neg_lo:[0,1] neg_hi:[0,1]
	v_pk_add_f32 v[46:47], v[46:47], v[50:51] op_sel_hi:[1,0] neg_lo:[0,1] neg_hi:[0,1]
	v_pk_add_f32 v[48:49], v[48:49], v[50:51] op_sel_hi:[1,0] neg_lo:[0,1] neg_hi:[0,1]
	v_pk_add_f32 v[44:45], v[44:45], v[50:51] op_sel_hi:[1,0] neg_lo:[0,1] neg_hi:[0,1]
	v_pk_mul_f32 v[50:51], v[34:35], v[34:35]
	v_pk_mul_f32 v[52:53], v[36:37], v[36:37]
	v_add_f32_e32 v50, v50, v51
	v_add_f32_e32 v50, v52, v50
	v_pk_mul_f32 v[54:55], v[38:39], v[38:39]
	v_add_f32_e32 v50, v53, v50
	v_add_f32_e32 v50, v54, v50
	v_pk_mul_f32 v[56:57], v[40:41], v[40:41]
	v_add_f32_e32 v50, v55, v50
	v_add_f32_e32 v50, v56, v50
	v_pk_mul_f32 v[58:59], v[42:43], v[42:43]
	v_add_f32_e32 v50, v57, v50
	v_add_f32_e32 v50, v58, v50
	v_pk_mul_f32 v[60:61], v[46:47], v[46:47]
	v_add_f32_e32 v50, v59, v50
	v_add_f32_e32 v50, v60, v50
	v_pk_mul_f32 v[62:63], v[48:49], v[48:49]
	v_add_f32_e32 v50, v61, v50
	v_add_f32_e32 v50, v62, v50
	v_pk_mul_f32 v[64:65], v[44:45], v[44:45]
	v_add_f32_e32 v50, v63, v50
	v_add_f32_e32 v50, v64, v50
	v_add_f32_e32 v50, v65, v50
	s_waitcnt lgkmcnt(0)
	s_nop 1
	v_add_f32_dpp v50, v50, v50 quad_perm:[1,0,3,2] row_mask:0xf bank_mask:0xf
	s_waitcnt lgkmcnt(0)
	s_nop 1
	v_add_f32_dpp v50, v50, v50 quad_perm:[2,3,0,1] row_mask:0xf bank_mask:0xf
	s_waitcnt lgkmcnt(0)
	s_nop 1
	v_add_f32_dpp v50, v50, v50 row_half_mirror row_mask:0xf bank_mask:0xf
	s_waitcnt lgkmcnt(0)
	s_nop 1
	v_add_f32_dpp v50, v50, v50 row_mirror row_mask:0xf bank_mask:0xf
	s_waitcnt lgkmcnt(0)
	v_mov_b32_e32 v51, v50
	s_nop 1
	v_permlane16_swap_b32_e32 v50, v51
	v_add_f32_e32 v50, v50, v51
	s_waitcnt lgkmcnt(0)
	v_mov_b32_e32 v51, v50
	s_nop 1
	v_permlane32_swap_b32_e32 v50, v51
	v_add_f32_e32 v50, v50, v51
	v_fmamk_f32 v50, v50, 0x3a800000, v164
	v_mul_f32_e32 v51, 0x4b800000, v50
	v_cmp_gt_f32_e32 vcc, s0, v50
	s_nop 1
	v_cndmask_b32_e32 v50, v50, v51, vcc
	v_rsq_f32_e32 v50, v50
	s_nop 0
	v_mul_f32_e32 v51, 0x45800000, v50
	v_cndmask_b32_e32 v50, v50, v51, vcc
	v_pk_mul_f32 v[34:35], v[34:35], v[50:51] op_sel_hi:[1,0]
	v_pk_mul_f32 v[36:37], v[36:37], v[50:51] op_sel_hi:[1,0]
	v_pk_mul_f32 v[38:39], v[38:39], v[50:51] op_sel_hi:[1,0]
	v_pk_mul_f32 v[40:41], v[40:41], v[50:51] op_sel_hi:[1,0]
	v_pk_mul_f32 v[52:53], v[42:43], v[50:51] op_sel_hi:[1,0]
	v_pk_mul_f32 v[54:55], v[46:47], v[50:51] op_sel_hi:[1,0]
	v_pk_mul_f32 v[56:57], v[48:49], v[50:51] op_sel_hi:[1,0]
	v_pk_mul_f32 v[50:51], v[44:45], v[50:51] op_sel_hi:[1,0]
	v_pk_fma_f32 v[46:47], v[2:3], v[34:35], v[10:11]
	v_pk_fma_f32 v[48:49], v[4:5], v[36:37], v[12:13]
	v_pk_fma_f32 v[42:43], v[6:7], v[38:39], v[14:15]
	v_pk_fma_f32 v[38:39], v[18:19], v[52:53], v[26:27]
	v_pk_fma_f32 v[36:37], v[24:25], v[50:51], v[32:33]
	v_and_b32_sdwa v51, v46, v171 dst_sel:DWORD dst_unused:UNUSED_PAD src0_sel:WORD_1 src1_sel:DWORD
	v_and_b32_sdwa v52, v49, v171 dst_sel:DWORD dst_unused:UNUSED_PAD src0_sel:WORD_1 src1_sel:DWORD
	v_and_b32_sdwa v53, v47, v171 dst_sel:DWORD dst_unused:UNUSED_PAD src0_sel:WORD_1 src1_sel:DWORD
	v_and_b32_sdwa v50, v48, v171 dst_sel:DWORD dst_unused:UNUSED_PAD src0_sel:WORD_1 src1_sel:DWORD
	v_add3_u32 v58, v46, v51, s84
	v_add3_u32 v51, v49, v52, s84
	v_add3_u32 v52, v47, v53, s84
	v_pk_fma_f32 v[44:45], v[8:9], v[40:41], v[16:17]
	v_add3_u32 v50, v48, v50, s84
	v_and_b32_e32 v51, 0xffff0000, v51
	v_and_b32_e32 v52, 0xffff0000, v52
	v_pk_fma_f32 v[40:41], v[20:21], v[54:55], v[28:29]
; __device__ __forceinline__ unsigned pk2(float lo, float hi) { return f2bf(lo) | (f2bf(hi) << 16); }
; __device__ __forceinline__ void phase_expert(CArgs& A, int l, unsigned char* lds, int tid, bool dry = false) {
;     ...
;         { bf16* xr = X + (size_t)t * DM + lane * 4;
; #pragma unroll
;           for (int i = 0; i < 4; ++i) { u32x2 w; w.x = pk2(s[4 * i], s[4 * i + 1]); w.y = pk2(s[4 * i + 2], s[4 * i + 3]); *(u32x2*)(xr + 256 * i) = w; } }
;         if (l == DEPTH - 1) {
	v_pk_fma_f32 v[34:35], v[22:23], v[56:57], v[30:31]
	v_and_b32_sdwa v55, v42, v171 dst_sel:DWORD dst_unused:UNUSED_PAD src0_sel:WORD_1 src1_sel:DWORD
	v_and_b32_sdwa v56, v45, v171 dst_sel:DWORD dst_unused:UNUSED_PAD src0_sel:WORD_1 src1_sel:DWORD
	v_and_b32_sdwa v57, v43, v171 dst_sel:DWORD dst_unused:UNUSED_PAD src0_sel:WORD_1 src1_sel:DWORD
	v_or_b32_sdwa v51, v51, v50 dst_sel:DWORD dst_unused:UNUSED_PAD src0_sel:DWORD src1_sel:WORD_1
	v_or_b32_sdwa v50, v52, v58 dst_sel:DWORD dst_unused:UNUSED_PAD src0_sel:DWORD src1_sel:WORD_1
	v_and_b32_sdwa v54, v44, v171 dst_sel:DWORD dst_unused:UNUSED_PAD src0_sel:WORD_1 src1_sel:DWORD
	v_add3_u32 v53, v42, v55, s84
	v_add3_u32 v55, v45, v56, s84
	global_store_dwordx2 v[138:139], v[50:51], off
	v_add3_u32 v50, v43, v57, s84
	v_add3_u32 v54, v44, v54, s84
	v_and_b32_e32 v51, 0xffff0000, v55
	v_and_b32_e32 v50, 0xffff0000, v50
	v_or_b32_sdwa v51, v51, v54 dst_sel:DWORD dst_unused:UNUSED_PAD src0_sel:DWORD src1_sel:WORD_1
	v_or_b32_sdwa v50, v50, v53 dst_sel:DWORD dst_unused:UNUSED_PAD src0_sel:DWORD src1_sel:WORD_1
	global_store_dwordx2 v[138:139], v[50:51], off offset:512
	v_and_b32_sdwa v51, v38, v171 dst_sel:DWORD dst_unused:UNUSED_PAD src0_sel:WORD_1 src1_sel:DWORD
	v_add3_u32 v52, v38, v51, s84
	v_and_b32_sdwa v51, v41, v171 dst_sel:DWORD dst_unused:UNUSED_PAD src0_sel:WORD_1 src1_sel:DWORD
	v_and_b32_sdwa v53, v39, v171 dst_sel:DWORD dst_unused:UNUSED_PAD src0_sel:WORD_1 src1_sel:DWORD
	v_and_b32_sdwa v50, v40, v171 dst_sel:DWORD dst_unused:UNUSED_PAD src0_sel:WORD_1 src1_sel:DWORD
	v_add3_u32 v51, v41, v51, s84
	v_add3_u32 v53, v39, v53, s84
	v_add3_u32 v50, v40, v50, s84
	v_and_b32_e32 v51, 0xffff0000, v51
	v_and_b32_e32 v53, 0xffff0000, v53
	v_or_b32_sdwa v51, v51, v50 dst_sel:DWORD dst_unused:UNUSED_PAD src0_sel:DWORD src1_sel:WORD_1
	v_or_b32_sdwa v50, v53, v52 dst_sel:DWORD dst_unused:UNUSED_PAD src0_sel:DWORD src1_sel:WORD_1
	global_store_dwordx2 v[138:139], v[50:51], off offset:1024
	v_and_b32_sdwa v51, v34, v171 dst_sel:DWORD dst_unused:UNUSED_PAD src0_sel:WORD_1 src1_sel:DWORD
	v_add3_u32 v52, v34, v51, s84
	v_and_b32_sdwa v51, v37, v171 dst_sel:DWORD dst_unused:UNUSED_PAD src0_sel:WORD_1 src1_sel:DWORD
	v_and_b32_sdwa v53, v35, v171 dst_sel:DWORD dst_unused:UNUSED_PAD src0_sel:WORD_1 src1_sel:DWORD
	v_and_b32_sdwa v50, v36, v171 dst_sel:DWORD dst_unused:UNUSED_PAD src0_sel:WORD_1 src1_sel:DWORD
	v_add3_u32 v51, v37, v51, s84
	v_add3_u32 v53, v35, v53, s84
	v_add3_u32 v50, v36, v50, s84
	v_and_b32_e32 v51, 0xffff0000, v51
	v_and_b32_e32 v53, 0xffff0000, v53
	v_or_b32_sdwa v51, v51, v50 dst_sel:DWORD dst_unused:UNUSED_PAD src0_sel:DWORD src1_sel:WORD_1
	v_or_b32_sdwa v50, v53, v52 dst_sel:DWORD dst_unused:UNUSED_PAD src0_sel:DWORD src1_sel:WORD_1
	s_and_b64 vcc, exec, s[58:59]
	global_store_dwordx2 v[138:139], v[50:51], off offset:1536
	s_cbranch_vccz .LBB0_121
; __device__ __forceinline__ void phase_expert(CArgs& A, int l, unsigned char* lds, int tid, bool dry = false) {
;     ...
;             float a0 = 0.f, a1 = 0.f, a2 = 0.f, a3 = 0.f;
; #pragma unroll
;             for (int i = 0; i < 16; ++i) { const int d = lane * 4 + 256 * (i >> 2) + (i & 3); const f32x4 w = *(const f32x4*)(lw + 4 * d + 4 * (d >> 3));
;                 a0 += s[i] * w.x; a1 += s[i] * w.y; a2 += s[i] * w.z; a3 += s[i] * w.w; }
;             a0 = wave_sum(a0); a1 = wave_sum(a1); a2 = wave_sum(a2); a3 = wave_sum(a3);
;             if (lane == 0) *(f32x4*)((float*)(A.ws + WS_FLOG) + (size_t)t * 4) = (f32x4){a0, a1, a2, a3};
	ds_read_b128 v[50:53], v197 offset:8192
	ds_read_b128 v[54:57], v197 offset:8208
	ds_read_b128 v[58:61], v197 offset:8224
	ds_read_b128 v[62:65], v197 offset:8240
	ds_read_b128 v[66:69], v198 offset:8192
	ds_read_b128 v[70:73], v199 offset:8192
	ds_read_b128 v[74:77], v200 offset:8192
	ds_read_b128 v[78:81], v201 offset:8192
	ds_read_b128 v[82:85], v202 offset:8192
	ds_read_b128 v[86:89], v203 offset:8192
	ds_read_b128 v[90:93], v204 offset:8192
	s_waitcnt lgkmcnt(10)
	v_pk_fma_f32 v[50:51], v[46:47], v[50:51], 0 op_sel_hi:[0,1,0]
	v_pk_fma_f32 v[52:53], v[46:47], v[52:53], 0 op_sel_hi:[0,1,0]
	s_waitcnt lgkmcnt(9)
	v_pk_fma_f32 v[50:51], v[46:47], v[54:55], v[50:51] op_sel:[1,0,0]
	v_pk_fma_f32 v[52:53], v[46:47], v[56:57], v[52:53] op_sel:[1,0,0]
	s_waitcnt lgkmcnt(8)
	v_pk_fma_f32 v[50:51], v[48:49], v[58:59], v[50:51] op_sel_hi:[0,1,1]
	v_pk_fma_f32 v[52:53], v[48:49], v[60:61], v[52:53] op_sel_hi:[0,1,1]
	s_waitcnt lgkmcnt(7)
	v_pk_fma_f32 v[50:51], v[48:49], v[62:63], v[50:51] op_sel:[1,0,0]
	v_pk_fma_f32 v[52:53], v[48:49], v[64:65], v[52:53] op_sel:[1,0,0]
	s_waitcnt lgkmcnt(6)
	v_pk_fma_f32 v[50:51], v[42:43], v[66:67], v[50:51] op_sel_hi:[0,1,1]
	v_pk_fma_f32 v[52:53], v[42:43], v[68:69], v[52:53] op_sel_hi:[0,1,1]
	s_waitcnt lgkmcnt(5)
	v_pk_fma_f32 v[50:51], v[42:43], v[70:71], v[50:51] op_sel:[1,0,0]
	v_pk_fma_f32 v[52:53], v[42:43], v[72:73], v[52:53] op_sel:[1,0,0]
	s_waitcnt lgkmcnt(4)
	v_pk_fma_f32 v[50:51], v[44:45], v[74:75], v[50:51] op_sel_hi:[0,1,1]
	v_pk_fma_f32 v[52:53], v[44:45], v[76:77], v[52:53] op_sel_hi:[0,1,1]
	s_waitcnt lgkmcnt(3)
	v_pk_fma_f32 v[50:51], v[44:45], v[78:79], v[50:51] op_sel:[1,0,0]
	v_pk_fma_f32 v[52:53], v[44:45], v[80:81], v[52:53] op_sel:[1,0,0]
	s_waitcnt lgkmcnt(2)
	v_pk_fma_f32 v[50:51], v[38:39], v[82:83], v[50:51] op_sel_hi:[0,1,1]
	v_pk_fma_f32 v[52:53], v[38:39], v[84:85], v[52:53] op_sel_hi:[0,1,1]
	s_waitcnt lgkmcnt(1)
	v_pk_fma_f32 v[50:51], v[38:39], v[86:87], v[50:51] op_sel:[1,0,0]
	v_pk_fma_f32 v[52:53], v[38:39], v[88:89], v[52:53] op_sel:[1,0,0]
	s_waitcnt lgkmcnt(0)
	v_pk_fma_f32 v[50:51], v[40:41], v[90:91], v[50:51] op_sel_hi:[0,1,1]
	v_pk_fma_f32 v[72:73], v[40:41], v[92:93], v[52:53] op_sel_hi:[0,1,1]
	ds_read_b128 v[52:55], v205 offset:8192
	ds_read_b128 v[56:59], v206 offset:8192
	ds_read_b128 v[60:63], v207 offset:8192
	ds_read_b128 v[64:67], v208 offset:8192
	ds_read_b128 v[68:71], v209 offset:8192
	s_waitcnt lgkmcnt(4)
	v_pk_fma_f32 v[50:51], v[40:41], v[52:53], v[50:51] op_sel:[1,0,0]
	v_pk_fma_f32 v[54:55], v[40:41], v[54:55], v[72:73] op_sel:[1,0,0]
	s_waitcnt lgkmcnt(3)
	v_pk_fma_f32 v[50:51], v[34:35], v[56:57], v[50:51] op_sel_hi:[0,1,1]
	v_pk_fma_f32 v[54:55], v[34:35], v[58:59], v[54:55] op_sel_hi:[0,1,1]
	s_waitcnt lgkmcnt(2)
	v_pk_fma_f32 v[50:51], v[34:35], v[60:61], v[50:51] op_sel:[1,0,0]
	v_pk_fma_f32 v[54:55], v[34:35], v[62:63], v[54:55] op_sel:[1,0,0]
	s_waitcnt lgkmcnt(1)
	v_pk_fma_f32 v[50:51], v[36:37], v[64:65], v[50:51] op_sel_hi:[0,1,1]
	v_pk_fma_f32 v[54:55], v[36:37], v[66:67], v[54:55] op_sel_hi:[0,1,1]
	s_waitcnt lgkmcnt(0)
	v_pk_fma_f32 v[50:51], v[36:37], v[68:69], v[50:51] op_sel:[1,0,0]
	v_pk_fma_f32 v[54:55], v[36:37], v[70:71], v[54:55] op_sel:[1,0,0]
	ds_bpermute_b32 v52, v143, v50
	ds_bpermute_b32 v53, v143, v51
	ds_bpermute_b32 v56, v143, v54
	ds_bpermute_b32 v57, v143, v55
	s_waitcnt lgkmcnt(2)
	v_pk_add_f32 v[50:51], v[50:51], v[52:53]
	ds_bpermute_b32 v52, v192, v50
	s_waitcnt lgkmcnt(1)
	v_pk_add_f32 v[54:55], v[54:55], v[56:57]
	ds_bpermute_b32 v53, v192, v51
	ds_bpermute_b32 v56, v192, v54
	ds_bpermute_b32 v57, v192, v55
	s_waitcnt lgkmcnt(2)
	v_pk_add_f32 v[50:51], v[50:51], v[52:53]
	ds_bpermute_b32 v52, v193, v50
	s_waitcnt lgkmcnt(1)
	v_pk_add_f32 v[54:55], v[54:55], v[56:57]
	ds_bpermute_b32 v53, v193, v51
	ds_bpermute_b32 v56, v193, v54
	ds_bpermute_b32 v57, v193, v55
	s_waitcnt lgkmcnt(2)
	v_pk_add_f32 v[50:51], v[50:51], v[52:53]
	ds_bpermute_b32 v52, v194, v50
	s_waitcnt lgkmcnt(1)
	v_pk_add_f32 v[54:55], v[54:55], v[56:57]
	ds_bpermute_b32 v53, v194, v51
	ds_bpermute_b32 v56, v194, v54
	ds_bpermute_b32 v57, v194, v55
	s_waitcnt lgkmcnt(2)
	v_pk_add_f32 v[50:51], v[50:51], v[52:53]
	ds_bpermute_b32 v52, v195, v50
	s_waitcnt lgkmcnt(1)
	v_pk_add_f32 v[54:55], v[54:55], v[56:57]
	ds_bpermute_b32 v53, v195, v51
	ds_bpermute_b32 v56, v195, v54
	ds_bpermute_b32 v57, v195, v55
	s_waitcnt lgkmcnt(2)
	v_pk_add_f32 v[50:51], v[50:51], v[52:53]
	ds_bpermute_b32 v52, v196, v50
	s_waitcnt lgkmcnt(1)
	v_pk_add_f32 v[54:55], v[54:55], v[56:57]
	ds_bpermute_b32 v53, v196, v51
	ds_bpermute_b32 v56, v196, v54
	ds_bpermute_b32 v57, v196, v55
	s_and_saveexec_b64 s[4:5], s[46:47]
	s_cbranch_execz .LBB0_120
	v_lshl_add_u64 v[58:59], v[126:127], 4, s[60:61]
	s_waitcnt lgkmcnt(0)
	v_pk_add_f32 v[54:55], v[54:55], v[56:57]
	v_pk_add_f32 v[52:53], v[50:51], v[52:53]
	global_store_dwordx4 v[58:59], v[52:55], off

; __device__ __forceinline__ void phase_ln(bf16* X, const bf16* Mx, const float* g, const float* b, int tid) {
;     ...
;         for (int u = 0; u < 4; ++u) { const int t = t0 + u * NGW; if (t < T) {
;             float x[16], m[16];
;             unpack8(xa[u][0], x); unpack8(xa[u][1], x + 8); unpack8(ma[u][0], m); unpack8(ma[u][1], m + 8);
;             float sum = 0.f;
; #pragma unroll
;             for (int i = 0; i < 16; ++i) { x[i] = ALPHA * x[i] + m[i]; sum += x[i]; }
;             const float mean = wave_sum(sum) * (1.f / DM);
;             float q = 0.f;
; #pragma unroll
;             for (int i = 0; i < 16; ++i) { x[i] -= mean; q += x[i] * x[i]; }
;             const float rstd = rsqrtf(wave_sum(q) * (1.f / DM) + LN_EPS);
; #pragma unroll
;             for (int i = 0; i < 16; ++i) x[i] = x[i] * rstd * gg[i] + bb[i];
.LBB0_159:
	s_or_b64 exec, exec, s[36:37]
	s_waitcnt vmcnt(3)
	v_lshlrev_b32_e32 v117, 16, v93
	v_lshlrev_b32_e32 v116, 16, v92
	s_waitcnt vmcnt(1)
	v_lshlrev_b32_e32 v122, 16, v88
	v_lshlrev_b32_e32 v123, 16, v89
	v_and_b32_e32 v128, 0xffff0000, v86
	v_lshlrev_b32_e32 v129, 16, v86
	s_waitcnt vmcnt(0)
	v_and_b32_e32 v130, 0xffff0000, v82
	v_lshlrev_b32_e32 v131, 16, v82
	s_mov_b32 s14, 0x3fb504f3
	v_and_b32_e32 v86, 0xffff0000, v87
	v_lshlrev_b32_e32 v87, 16, v87
	v_and_b32_e32 v82, 0xffff0000, v83
	v_lshlrev_b32_e32 v83, 16, v83
	v_and_b32_e32 v93, 0xffff0000, v93
	v_and_b32_e32 v92, 0xffff0000, v92
	v_and_b32_e32 v88, 0xffff0000, v88
	v_and_b32_e32 v89, 0xffff0000, v89
	v_pk_fma_f32 v[82:83], v[86:87], s[14:15], v[82:83] op_sel_hi:[1,0,1]
	v_pk_fma_f32 v[86:87], v[116:117], s[14:15], v[122:123] op_sel_hi:[1,0,1]
	v_pk_fma_f32 v[88:89], v[92:93], s[14:15], v[88:89] op_sel_hi:[1,0,1]
	v_add_f32_e32 v115, 0, v86
	v_add_f32_e32 v92, v88, v115
	v_lshlrev_b32_e32 v119, 16, v95
	v_lshlrev_b32_e32 v118, 16, v94
	v_lshlrev_b32_e32 v124, 16, v90
	v_lshlrev_b32_e32 v125, 16, v91
	v_add_f32_e32 v92, v87, v92
	v_and_b32_e32 v95, 0xffff0000, v95
	v_and_b32_e32 v94, 0xffff0000, v94
	v_and_b32_e32 v90, 0xffff0000, v90
	v_and_b32_e32 v91, 0xffff0000, v91
	v_add_f32_e32 v115, v89, v92
	v_pk_fma_f32 v[92:93], v[118:119], s[14:15], v[124:125] op_sel_hi:[1,0,1]
	v_pk_fma_f32 v[90:91], v[94:95], s[14:15], v[90:91] op_sel_hi:[1,0,1]
	v_add_f32_e32 v94, v92, v115
	v_add_f32_e32 v94, v90, v94
	v_lshlrev_b32_e32 v121, 16, v85
	v_lshlrev_b32_e32 v120, 16, v84
	v_lshlrev_b32_e32 v126, 16, v80
	v_lshlrev_b32_e32 v127, 16, v81
	v_add_f32_e32 v94, v93, v94
	v_and_b32_e32 v85, 0xffff0000, v85
	v_and_b32_e32 v84, 0xffff0000, v84
	v_and_b32_e32 v80, 0xffff0000, v80
	v_and_b32_e32 v81, 0xffff0000, v81
	v_add_f32_e32 v115, v91, v94
	v_pk_fma_f32 v[94:95], v[120:121], s[14:15], v[126:127] op_sel_hi:[1,0,1]
	v_pk_fma_f32 v[80:81], v[84:85], s[14:15], v[80:81] op_sel_hi:[1,0,1]
	v_add_f32_e32 v84, v94, v115
	v_add_f32_e32 v84, v80, v84
	v_add_f32_e32 v84, v95, v84
	v_pk_fma_f32 v[128:129], v[128:129], s[14:15], v[130:131] op_sel_hi:[1,0,1]
	v_add_f32_e32 v84, v81, v84
	v_add_f32_e32 v84, v129, v84
	v_add_f32_e32 v84, v128, v84
	v_add_f32_e32 v84, v83, v84
	v_add_f32_e32 v84, v82, v84
	v_mov_b32_e32 v130, v129
	v_mov_b32_e32 v131, v83
	v_mov_b32_e32 v129, v82
	s_mov_b32 s9, 0x800000
	s_waitcnt lgkmcnt(0)
	s_nop 1
	v_add_f32_dpp v84, v84, v84 quad_perm:[1,0,3,2] row_mask:0xf bank_mask:0xf
	s_waitcnt lgkmcnt(0)
	s_nop 1
	v_add_f32_dpp v84, v84, v84 quad_perm:[2,3,0,1] row_mask:0xf bank_mask:0xf
	s_waitcnt lgkmcnt(0)
	s_nop 1
	v_add_f32_dpp v84, v84, v84 row_half_mirror row_mask:0xf bank_mask:0xf
	s_waitcnt lgkmcnt(0)
	s_nop 1
	v_add_f32_dpp v84, v84, v84 row_mirror row_mask:0xf bank_mask:0xf
	s_waitcnt lgkmcnt(0)
	v_mov_b32_e32 v85, v84
	s_nop 1
	v_permlane16_swap_b32_e32 v84, v85
	v_add_f32_e32 v84, v84, v85
	s_waitcnt lgkmcnt(0)
	v_mov_b32_e32 v85, v84
	s_nop 1
	v_permlane32_swap_b32_e32 v84, v85
	v_add_f32_e32 v84, v84, v85
	v_mul_f32_e32 v84, 0x3a800000, v84
	v_pk_add_f32 v[86:87], v[86:87], v[84:85] op_sel_hi:[1,0] neg_lo:[0,1] neg_hi:[0,1]
	v_pk_add_f32 v[88:89], v[88:89], v[84:85] op_sel_hi:[1,0] neg_lo:[0,1] neg_hi:[0,1]
	v_pk_mul_f32 v[116:117], v[86:87], v[86:87]
	v_pk_mul_f32 v[118:119], v[88:89], v[88:89]
	v_pk_add_f32 v[92:93], v[92:93], v[84:85] op_sel_hi:[1,0] neg_lo:[0,1] neg_hi:[0,1]
	v_add_f32_e32 v115, v116, v118
	v_add_f32_e32 v115, v117, v115
	v_pk_mul_f32 v[120:121], v[92:93], v[92:93]
	v_pk_add_f32 v[90:91], v[90:91], v[84:85] op_sel_hi:[1,0] neg_lo:[0,1] neg_hi:[0,1]
	v_add_f32_e32 v115, v119, v115
	v_pk_mul_f32 v[122:123], v[90:91], v[90:91]
	v_add_f32_e32 v115, v120, v115
	v_add_f32_e32 v115, v122, v115
	v_pk_add_f32 v[94:95], v[94:95], v[84:85] op_sel_hi:[1,0] neg_lo:[0,1] neg_hi:[0,1]
	v_add_f32_e32 v115, v121, v115
	v_pk_mul_f32 v[124:125], v[94:95], v[94:95]
	v_pk_add_f32 v[80:81], v[80:81], v[84:85] op_sel_hi:[1,0] neg_lo:[0,1] neg_hi:[0,1]
	v_add_f32_e32 v115, v123, v115
	v_pk_mul_f32 v[126:127], v[80:81], v[80:81]
	v_add_f32_e32 v115, v124, v115
	v_pk_add_f32 v[130:131], v[130:131], v[84:85] op_sel_hi:[1,0] neg_lo:[0,1] neg_hi:[0,1]
	v_pk_add_f32 v[82:83], v[128:129], v[84:85] op_sel_hi:[1,0] neg_lo:[0,1] neg_hi:[0,1]
	v_add_f32_e32 v115, v126, v115
	v_mov_b32_e32 v84, v82
	v_mov_b32_e32 v85, v130
	v_add_f32_e32 v115, v125, v115
	v_pk_mul_f32 v[84:85], v[84:85], v[84:85]
	v_add_f32_e32 v115, v127, v115
	v_mov_b32_e32 v128, v83
	v_mov_b32_e32 v129, v131
	v_add_f32_e32 v85, v85, v115
	v_pk_mul_f32 v[128:129], v[128:129], v[128:129]
	v_add_f32_e32 v84, v84, v85
	v_add_f32_e32 v84, v129, v84
	v_add_f32_e32 v84, v128, v84
	s_waitcnt lgkmcnt(0)
	s_nop 1
	v_add_f32_dpp v84, v84, v84 quad_perm:[1,0,3,2] row_mask:0xf bank_mask:0xf
	s_waitcnt lgkmcnt(0)
	s_nop 1
	v_add_f32_dpp v84, v84, v84 quad_perm:[2,3,0,1] row_mask:0xf bank_mask:0xf
	s_waitcnt lgkmcnt(0)
	s_nop 1
	v_add_f32_dpp v84, v84, v84 row_half_mirror row_mask:0xf bank_mask:0xf
	s_waitcnt lgkmcnt(0)
	s_nop 1
	v_add_f32_dpp v84, v84, v84 row_mirror row_mask:0xf bank_mask:0xf
	s_waitcnt lgkmcnt(0)
	v_mov_b32_e32 v85, v84
	s_nop 1
	v_permlane16_swap_b32_e32 v84, v85
	v_add_f32_e32 v84, v84, v85
	s_waitcnt lgkmcnt(0)
; __device__ __forceinline__ void phase_ln(bf16* X, const bf16* Mx, const float* g, const float* b, int tid) {
;     ...
;         for (int u = 0; u < 4; ++u) { const int t = t0 + u * NGW; if (t < T) {
;             float x[16], m[16];
;             unpack8(xa[u][0], x); unpack8(xa[u][1], x + 8); unpack8(ma[u][0], m); unpack8(ma[u][1], m + 8);
;             float sum = 0.f;
; #pragma unroll
;             for (int i = 0; i < 16; ++i) { x[i] = ALPHA * x[i] + m[i]; sum += x[i]; }
;             const float mean = wave_sum(sum) * (1.f / DM);
;             float q = 0.f;
; #pragma unroll
;             for (int i = 0; i < 16; ++i) { x[i] -= mean; q += x[i] * x[i]; }
;             const float rstd = rsqrtf(wave_sum(q) * (1.f / DM) + LN_EPS);
; #pragma unroll
;             for (int i = 0; i < 16; ++i) x[i] = x[i] * rstd * gg[i] + bb[i];
;             store_row_bf16(X + (size_t)t * DM, lane, x); } }
	v_mov_b32_e32 v85, v84
	s_nop 1
	v_permlane32_swap_b32_e32 v84, v85
	v_add_f32_e32 v84, v84, v85
	v_fmamk_f32 v84, v84, 0x3a800000, v164
	v_mul_f32_e32 v85, 0x4b800000, v84
	v_cmp_gt_f32_e64 s[44:45], s9, v84
	s_nop 1
	v_cndmask_b32_e64 v84, v84, v85, s[44:45]
	v_rsq_f32_e32 v84, v84
	s_nop 0
	v_mul_f32_e32 v85, 0x45800000, v84
	v_cndmask_b32_e64 v84, v84, v85, s[44:45]
	v_pk_mul_f32 v[80:81], v[80:81], v[84:85] op_sel_hi:[1,0]
	v_pk_mul_f32 v[88:89], v[88:89], v[84:85] op_sel_hi:[1,0]
	v_pk_mul_f32 v[90:91], v[90:91], v[84:85] op_sel_hi:[1,0]
	v_pk_fma_f32 v[116:117], v[28:29], v[80:81], v[12:13]
	v_pk_mul_f32 v[80:81], v[130:131], v[84:85] op_sel_hi:[1,0]
	v_pk_mul_f32 v[86:87], v[86:87], v[84:85] op_sel_hi:[1,0]
	v_pk_fma_f32 v[88:89], v[98:99], v[88:89], v[96:97]
	v_pk_mul_f32 v[92:93], v[92:93], v[84:85] op_sel_hi:[1,0]
	v_pk_fma_f32 v[90:91], v[100:101], v[90:91], v[16:17]
	v_pk_fma_f32 v[118:119], v[18:19], v[80:81], v[2:3]
	v_pk_mul_f32 v[80:81], v[82:83], v[84:85] op_sel_hi:[1,0]
	v_pk_fma_f32 v[86:87], v[30:31], v[86:87], v[14:15]
	v_pk_fma_f32 v[92:93], v[26:27], v[92:93], v[10:11]
	v_pk_mul_f32 v[94:95], v[94:95], v[84:85] op_sel_hi:[1,0]
	v_pk_fma_f32 v[84:85], v[24:25], v[80:81], v[8:9]
	v_bfe_u32 v80, v91, 16, 1
	v_bfe_u32 v81, v90, 16, 1
	v_bfe_u32 v82, v89, 16, 1
	v_bfe_u32 v83, v88, 16, 1
	v_add3_u32 v88, v88, v83, s84
	v_add3_u32 v89, v89, v82, s84
	v_add3_u32 v81, v90, v81, s84
	v_add3_u32 v80, v91, v80, s84
	v_bfe_u32 v82, v86, 16, 1
	v_bfe_u32 v83, v87, 16, 1
	v_bfe_u32 v90, v92, 16, 1
	v_bfe_u32 v91, v93, 16, 1
	v_add3_u32 v91, v93, v91, s84
	v_add3_u32 v90, v92, v90, s84
	v_add3_u32 v83, v87, v83, s84
	v_add3_u32 v82, v86, v82, s84
	v_lshrrev_b32_e32 v86, 16, v82
	v_lshrrev_b32_e32 v87, 16, v83
	v_lshrrev_b32_e32 v82, 16, v90
	v_lshrrev_b32_e32 v83, 16, v91
	v_and_or_b32 v83, v80, s3, v83
	v_and_or_b32 v82, v81, s3, v82
	v_and_or_b32 v81, v89, s3, v87
	v_and_or_b32 v80, v88, s3, v86
	v_pk_fma_f32 v[94:95], v[22:23], v[94:95], v[6:7]
	global_store_dwordx4 v[108:109], v[80:83], off
	s_nop 1
	v_bfe_u32 v80, v85, 16, 1
	v_bfe_u32 v81, v84, 16, 1
	v_bfe_u32 v82, v117, 16, 1
	v_bfe_u32 v83, v116, 16, 1
	v_add3_u32 v86, v116, v83, s84
	v_add3_u32 v87, v117, v82, s84
	v_add3_u32 v81, v84, v81, s84
	v_add3_u32 v80, v85, v80, s84
	v_bfe_u32 v82, v94, 16, 1
	v_bfe_u32 v83, v95, 16, 1
	v_bfe_u32 v84, v118, 16, 1
	v_bfe_u32 v85, v119, 16, 1
	v_add3_u32 v85, v119, v85, s84
	v_add3_u32 v84, v118, v84, s84
	v_add3_u32 v83, v95, v83, s84
	v_add3_u32 v82, v94, v82, s84
	v_lshrrev_b32_e32 v88, 16, v82
	v_lshrrev_b32_e32 v89, 16, v83
	v_lshrrev_b32_e32 v82, 16, v84
	v_lshrrev_b32_e32 v83, 16, v85
	v_and_or_b32 v83, v80, s3, v83
	v_and_or_b32 v82, v81, s3, v82
	v_and_or_b32 v81, v87, s3, v89
	v_and_or_b32 v80, v86, s3, v88
	global_store_dwordx4 v[108:109], v[80:83], off offset:1024
	s_and_saveexec_b64 s[36:37], s[42:43]
	s_cbranch_execz .LBB0_162
	v_lshlrev_b32_e32 v81, 16, v53
	v_lshlrev_b32_e32 v80, 16, v52
	v_lshlrev_b32_e32 v92, 16, v76
	v_lshlrev_b32_e32 v93, 16, v77
	v_and_b32_e32 v83, 0xffff0000, v53
	v_and_b32_e32 v82, 0xffff0000, v52
	v_and_b32_e32 v94, 0xffff0000, v76
	v_and_b32_e32 v95, 0xffff0000, v77
	v_pk_fma_f32 v[80:81], v[80:81], s[14:15], v[92:93] op_sel_hi:[1,0,1]
	v_pk_fma_f32 v[82:83], v[82:83], s[14:15], v[94:95] op_sel_hi:[1,0,1]
	v_add_f32_e32 v92, 0, v80
	v_add_f32_e32 v92, v82, v92
	v_lshlrev_b32_e32 v85, 16, v55
	v_lshlrev_b32_e32 v84, 16, v54
	v_lshlrev_b32_e32 v108, 16, v78
	v_lshlrev_b32_e32 v109, 16, v79
	v_add_f32_e32 v92, v81, v92
	v_and_b32_e32 v87, 0xffff0000, v55
	v_and_b32_e32 v86, 0xffff0000, v54
	v_and_b32_e32 v116, 0xffff0000, v78
	v_and_b32_e32 v117, 0xffff0000, v79
	v_add_f32_e32 v92, v83, v92
	v_pk_fma_f32 v[84:85], v[84:85], s[14:15], v[108:109] op_sel_hi:[1,0,1]
	v_pk_fma_f32 v[86:87], v[86:87], s[14:15], v[116:117] op_sel_hi:[1,0,1]
	v_add_f32_e32 v92, v84, v92
	v_add_f32_e32 v92, v86, v92
	v_lshlrev_b32_e32 v89, 16, v49
	v_lshlrev_b32_e32 v88, 16, v48
	v_lshlrev_b32_e32 v118, 16, v72
	v_lshlrev_b32_e32 v119, 16, v73
	v_add_f32_e32 v92, v85, v92
	v_and_b32_e32 v91, 0xffff0000, v49
	v_and_b32_e32 v90, 0xffff0000, v48
	v_and_b32_e32 v120, 0xffff0000, v72
	v_and_b32_e32 v121, 0xffff0000, v73
	v_add_f32_e32 v92, v87, v92
	v_pk_fma_f32 v[88:89], v[88:89], s[14:15], v[118:119] op_sel_hi:[1,0,1]
	v_pk_fma_f32 v[90:91], v[90:91], s[14:15], v[120:121] op_sel_hi:[1,0,1]
	v_add_f32_e32 v92, v88, v92
	v_add_f32_e32 v92, v90, v92
	v_and_b32_e32 v122, 0xffff0000, v50
	v_lshlrev_b32_e32 v123, 16, v50
	v_and_b32_e32 v124, 0xffff0000, v74
	v_lshlrev_b32_e32 v125, 16, v74
	v_add_f32_e32 v92, v89, v92
	v_pk_fma_f32 v[122:123], v[122:123], s[14:15], v[124:125] op_sel_hi:[1,0,1]
	v_add_f32_e32 v92, v91, v92
	v_and_b32_e32 v124, 0xffff0000, v51
	v_lshlrev_b32_e32 v125, 16, v51
	v_and_b32_e32 v126, 0xffff0000, v75
	v_lshlrev_b32_e32 v127, 16, v75
	v_add_f32_e32 v92, v123, v92
	v_pk_fma_f32 v[124:125], v[124:125], s[14:15], v[126:127] op_sel_hi:[1,0,1]
	v_add_f32_e32 v92, v122, v92
	v_add_f32_e32 v92, v125, v92
	v_add_f32_e32 v92, v124, v92
	v_mov_b32_e32 v128, v123
	v_mov_b32_e32 v129, v125
	v_mov_b32_e32 v123, v124
	s_waitcnt lgkmcnt(0)
	s_nop 1
	v_add_f32_dpp v92, v92, v92 quad_perm:[1,0,3,2] row_mask:0xf bank_mask:0xf
	s_waitcnt lgkmcnt(0)
	s_nop 1
	v_add_f32_dpp v92, v92, v92 quad_perm:[2,3,0,1] row_mask:0xf bank_mask:0xf
	s_waitcnt lgkmcnt(0)
	s_nop 1
	v_add_f32_dpp v92, v92, v92 row_half_mirror row_mask:0xf bank_mask:0xf
	s_waitcnt lgkmcnt(0)
; __device__ __forceinline__ void phase_ln(bf16* X, const bf16* Mx, const float* g, const float* b, int tid) {
;     ...
;         for (int u = 0; u < 4; ++u) { const int t = t0 + u * NGW; if (t < T) {
;             float x[16], m[16];
;             unpack8(xa[u][0], x); unpack8(xa[u][1], x + 8); unpack8(ma[u][0], m); unpack8(ma[u][1], m + 8);
;             float sum = 0.f;
; #pragma unroll
;             for (int i = 0; i < 16; ++i) { x[i] = ALPHA * x[i] + m[i]; sum += x[i]; }
;             const float mean = wave_sum(sum) * (1.f / DM);
;             float q = 0.f;
; #pragma unroll
;             for (int i = 0; i < 16; ++i) { x[i] -= mean; q += x[i] * x[i]; }
;             const float rstd = rsqrtf(wave_sum(q) * (1.f / DM) + LN_EPS);
; #pragma unroll
;             for (int i = 0; i < 16; ++i) x[i] = x[i] * rstd * gg[i] + bb[i];
;             store_row_bf16(X + (size_t)t * DM, lane, x); } }
	s_nop 1
	v_add_f32_dpp v92, v92, v92 row_mirror row_mask:0xf bank_mask:0xf
	s_waitcnt lgkmcnt(0)
	v_mov_b32_e32 v93, v92
	s_nop 1
	v_permlane16_swap_b32_e32 v92, v93
	v_add_f32_e32 v92, v92, v93
	s_waitcnt lgkmcnt(0)
	v_mov_b32_e32 v93, v92
	s_nop 1
	v_permlane32_swap_b32_e32 v92, v93
	v_add_f32_e32 v92, v92, v93
	v_mul_f32_e32 v92, 0x3a800000, v92
	v_pk_add_f32 v[80:81], v[80:81], v[92:93] op_sel_hi:[1,0] neg_lo:[0,1] neg_hi:[0,1]
	v_pk_add_f32 v[82:83], v[82:83], v[92:93] op_sel_hi:[1,0] neg_lo:[0,1] neg_hi:[0,1]
	v_pk_mul_f32 v[94:95], v[80:81], v[80:81]
	v_pk_mul_f32 v[108:109], v[82:83], v[82:83]
	v_pk_add_f32 v[84:85], v[84:85], v[92:93] op_sel_hi:[1,0] neg_lo:[0,1] neg_hi:[0,1]
	v_add_f32_e32 v94, v94, v108
	v_add_f32_e32 v94, v95, v94
	v_pk_mul_f32 v[116:117], v[84:85], v[84:85]
	v_pk_add_f32 v[86:87], v[86:87], v[92:93] op_sel_hi:[1,0] neg_lo:[0,1] neg_hi:[0,1]
	v_add_f32_e32 v94, v109, v94
	v_pk_mul_f32 v[118:119], v[86:87], v[86:87]
	v_add_f32_e32 v94, v116, v94
	v_add_f32_e32 v94, v118, v94
	v_pk_add_f32 v[88:89], v[88:89], v[92:93] op_sel_hi:[1,0] neg_lo:[0,1] neg_hi:[0,1]
	v_add_f32_e32 v94, v117, v94
	v_pk_mul_f32 v[120:121], v[88:89], v[88:89]
	v_pk_add_f32 v[90:91], v[90:91], v[92:93] op_sel_hi:[1,0] neg_lo:[0,1] neg_hi:[0,1]
	v_add_f32_e32 v94, v119, v94
	v_pk_mul_f32 v[126:127], v[90:91], v[90:91]
	v_add_f32_e32 v94, v120, v94
	v_pk_add_f32 v[128:129], v[128:129], v[92:93] op_sel_hi:[1,0] neg_lo:[0,1] neg_hi:[0,1]
	v_pk_add_f32 v[92:93], v[122:123], v[92:93] op_sel_hi:[1,0] neg_lo:[0,1] neg_hi:[0,1]
	v_add_f32_e32 v94, v126, v94
	v_mov_b32_e32 v122, v92
	v_mov_b32_e32 v123, v128
	v_add_f32_e32 v94, v121, v94
	v_pk_mul_f32 v[122:123], v[122:123], v[122:123]
	v_add_f32_e32 v94, v127, v94
	v_mov_b32_e32 v124, v93
	v_mov_b32_e32 v125, v129
	v_add_f32_e32 v94, v123, v94
	v_pk_mul_f32 v[124:125], v[124:125], v[124:125]
	v_add_f32_e32 v94, v122, v94
	v_add_f32_e32 v94, v125, v94
	v_add_f32_e32 v94, v124, v94
	s_waitcnt lgkmcnt(0)
	s_nop 1
	v_add_f32_dpp v94, v94, v94 quad_perm:[1,0,3,2] row_mask:0xf bank_mask:0xf
	s_waitcnt lgkmcnt(0)
	s_nop 1
	v_add_f32_dpp v94, v94, v94 quad_perm:[2,3,0,1] row_mask:0xf bank_mask:0xf
	s_waitcnt lgkmcnt(0)
	s_nop 1
	v_add_f32_dpp v94, v94, v94 row_half_mirror row_mask:0xf bank_mask:0xf
	s_waitcnt lgkmcnt(0)
	s_nop 1
	v_add_f32_dpp v94, v94, v94 row_mirror row_mask:0xf bank_mask:0xf
	s_waitcnt lgkmcnt(0)
	v_mov_b32_e32 v95, v94
	s_nop 1
	v_permlane16_swap_b32_e32 v94, v95
	v_add_f32_e32 v94, v94, v95
	s_waitcnt lgkmcnt(0)
	v_mov_b32_e32 v95, v94
	s_nop 1
	v_permlane32_swap_b32_e32 v94, v95
	v_add_f32_e32 v94, v94, v95
	v_fmamk_f32 v94, v94, 0x3a800000, v164
	v_mul_f32_e32 v95, 0x4b800000, v94
	v_cmp_gt_f32_e64 s[42:43], s9, v94
	s_nop 1
	v_cndmask_b32_e64 v94, v94, v95, s[42:43]
	v_rsq_f32_e32 v108, v94
	v_lshlrev_b64 v[94:95], 11, v[102:103]
	v_lshl_add_u64 v[94:95], v[4:5], 0, v[94:95]
	v_mul_f32_e32 v103, 0x45800000, v108
	v_cndmask_b32_e64 v108, v108, v103, s[42:43]
	v_pk_mul_f32 v[82:83], v[82:83], v[108:109] op_sel_hi:[1,0]
	v_pk_mul_f32 v[86:87], v[86:87], v[108:109] op_sel_hi:[1,0]
	v_pk_mul_f32 v[80:81], v[80:81], v[108:109] op_sel_hi:[1,0]
	v_pk_fma_f32 v[82:83], v[98:99], v[82:83], v[96:97]
	v_pk_mul_f32 v[84:85], v[84:85], v[108:109] op_sel_hi:[1,0]
	v_pk_fma_f32 v[86:87], v[100:101], v[86:87], v[16:17]
	v_pk_fma_f32 v[80:81], v[30:31], v[80:81], v[14:15]
	v_pk_fma_f32 v[84:85], v[26:27], v[84:85], v[10:11]
	v_pk_mul_f32 v[88:89], v[88:89], v[108:109] op_sel_hi:[1,0]
	v_pk_mul_f32 v[90:91], v[90:91], v[108:109] op_sel_hi:[1,0]
	v_pk_mul_f32 v[116:117], v[128:129], v[108:109] op_sel_hi:[1,0]
	v_pk_mul_f32 v[92:93], v[92:93], v[108:109] op_sel_hi:[1,0]
	v_bfe_u32 v103, v87, 16, 1
	v_bfe_u32 v108, v86, 16, 1
	v_bfe_u32 v109, v83, 16, 1
	v_bfe_u32 v115, v82, 16, 1
	v_add3_u32 v115, v82, v115, s84
	v_add3_u32 v109, v83, v109, s84
	v_add3_u32 v82, v86, v108, s84
	v_add3_u32 v83, v87, v103, s84
	v_bfe_u32 v86, v80, 16, 1
	v_bfe_u32 v87, v81, 16, 1
	v_bfe_u32 v103, v84, 16, 1
	v_bfe_u32 v108, v85, 16, 1
	v_add3_u32 v85, v85, v108, s84
	v_add3_u32 v84, v84, v103, s84
	v_add3_u32 v81, v81, v87, s84
	v_add3_u32 v80, v80, v86, s84
	v_lshrrev_b32_e32 v80, 16, v80
	v_lshrrev_b32_e32 v81, 16, v81
	v_lshrrev_b32_e32 v84, 16, v84
	v_lshrrev_b32_e32 v85, 16, v85
	v_pk_fma_f32 v[90:91], v[28:29], v[90:91], v[12:13]
	v_and_or_b32 v83, v83, s3, v85
	v_and_or_b32 v82, v82, s3, v84
	v_and_or_b32 v81, v109, s3, v81
	v_and_or_b32 v80, v115, s3, v80
	v_pk_fma_f32 v[88:89], v[22:23], v[88:89], v[6:7]
	v_pk_fma_f32 v[116:117], v[18:19], v[116:117], v[2:3]
	global_store_dwordx4 v[94:95], v[80:83], off
	v_pk_fma_f32 v[92:93], v[24:25], v[92:93], v[8:9]
	v_bfe_u32 v86, v116, 16, 1
	v_bfe_u32 v82, v91, 16, 1
	v_bfe_u32 v83, v90, 16, 1
	v_add3_u32 v84, v90, v83, s84
	v_add3_u32 v85, v91, v82, s84
	v_bfe_u32 v82, v88, 16, 1
	v_bfe_u32 v83, v89, 16, 1
	v_bfe_u32 v87, v117, 16, 1
	v_bfe_u32 v80, v93, 16, 1
	v_bfe_u32 v81, v92, 16, 1
	v_add3_u32 v87, v117, v87, s84
	v_add3_u32 v86, v116, v86, s84
	v_add3_u32 v83, v89, v83, s84
	v_add3_u32 v82, v88, v82, s84
	v_add3_u32 v81, v92, v81, s84
	v_add3_u32 v80, v93, v80, s84
	v_lshrrev_b32_e32 v88, 16, v82
	v_lshrrev_b32_e32 v89, 16, v83
	v_lshrrev_b32_e32 v82, 16, v86
	v_lshrrev_b32_e32 v83, 16, v87
	v_and_or_b32 v83, v80, s3, v83
	v_and_or_b32 v82, v81, s3, v82
	v_and_or_b32 v81, v85, s3, v89
	v_and_or_b32 v80, v84, s3, v88
	global_store_dwordx4 v[94:95], v[80:83], off offset:1024
	s_or_b64 exec, exec, s[36:37]
	s_and_saveexec_b64 s[36:37], s[40:41]
	s_cbranch_execnz .LBB0_163

; __device__ __forceinline__ void phase_ln(bf16* X, const bf16* Mx, const float* g, const float* b, int tid) {
;     ...
;         for (int u = 0; u < 4; ++u) { const int t = t0 + u * NGW; if (t < T) {
;             float x[16], m[16];
;             unpack8(xa[u][0], x); unpack8(xa[u][1], x + 8); unpack8(ma[u][0], m); unpack8(ma[u][1], m + 8);
;             float sum = 0.f;
; #pragma unroll
;             for (int i = 0; i < 16; ++i) { x[i] = ALPHA * x[i] + m[i]; sum += x[i]; }
;             const float mean = wave_sum(sum) * (1.f / DM);
;             float q = 0.f;
; #pragma unroll
;             for (int i = 0; i < 16; ++i) { x[i] -= mean; q += x[i] * x[i]; }
;             const float rstd = rsqrtf(wave_sum(q) * (1.f / DM) + LN_EPS);
; #pragma unroll
;             for (int i = 0; i < 16; ++i) x[i] = x[i] * rstd * gg[i] + bb[i];
.LBB0_163:
	v_lshlrev_b32_e32 v81, 16, v45
	v_lshlrev_b32_e32 v80, 16, v44
	v_lshlrev_b32_e32 v92, 16, v68
	v_lshlrev_b32_e32 v93, 16, v69
	v_and_b32_e32 v83, 0xffff0000, v45
	v_and_b32_e32 v82, 0xffff0000, v44
	v_and_b32_e32 v94, 0xffff0000, v68
	v_and_b32_e32 v95, 0xffff0000, v69
	v_pk_fma_f32 v[80:81], v[80:81], s[14:15], v[92:93] op_sel_hi:[1,0,1]
	v_pk_fma_f32 v[82:83], v[82:83], s[14:15], v[94:95] op_sel_hi:[1,0,1]
	v_add_f32_e32 v92, 0, v80
	v_add_f32_e32 v92, v82, v92
	v_lshlrev_b32_e32 v85, 16, v47
	v_lshlrev_b32_e32 v84, 16, v46
	v_lshlrev_b32_e32 v108, 16, v70
	v_lshlrev_b32_e32 v109, 16, v71
	v_add_f32_e32 v92, v81, v92
	v_and_b32_e32 v87, 0xffff0000, v47
	v_and_b32_e32 v86, 0xffff0000, v46
	v_and_b32_e32 v116, 0xffff0000, v70
	v_and_b32_e32 v117, 0xffff0000, v71
	v_add_f32_e32 v92, v83, v92
	v_pk_fma_f32 v[84:85], v[84:85], s[14:15], v[108:109] op_sel_hi:[1,0,1]
	v_pk_fma_f32 v[86:87], v[86:87], s[14:15], v[116:117] op_sel_hi:[1,0,1]
	v_add_f32_e32 v92, v84, v92
	v_add_f32_e32 v92, v86, v92
	v_lshlrev_b32_e32 v89, 16, v41
	v_lshlrev_b32_e32 v88, 16, v40
	v_lshlrev_b32_e32 v118, 16, v64
	v_lshlrev_b32_e32 v119, 16, v65
	v_add_f32_e32 v92, v85, v92
	v_and_b32_e32 v91, 0xffff0000, v41
	v_and_b32_e32 v90, 0xffff0000, v40
	v_and_b32_e32 v120, 0xffff0000, v64
	v_and_b32_e32 v121, 0xffff0000, v65
	v_add_f32_e32 v92, v87, v92
	v_pk_fma_f32 v[88:89], v[88:89], s[14:15], v[118:119] op_sel_hi:[1,0,1]
	v_pk_fma_f32 v[90:91], v[90:91], s[14:15], v[120:121] op_sel_hi:[1,0,1]
	v_add_f32_e32 v92, v88, v92
	v_add_f32_e32 v92, v90, v92
	v_and_b32_e32 v122, 0xffff0000, v42
	v_lshlrev_b32_e32 v123, 16, v42
	v_and_b32_e32 v124, 0xffff0000, v66
	v_lshlrev_b32_e32 v125, 16, v66
	v_add_f32_e32 v92, v89, v92
	v_pk_fma_f32 v[122:123], v[122:123], s[14:15], v[124:125] op_sel_hi:[1,0,1]
	v_add_f32_e32 v92, v91, v92
	v_and_b32_e32 v124, 0xffff0000, v43
	v_lshlrev_b32_e32 v125, 16, v43
	v_and_b32_e32 v126, 0xffff0000, v67
	v_lshlrev_b32_e32 v127, 16, v67
	v_add_f32_e32 v92, v123, v92
	v_pk_fma_f32 v[124:125], v[124:125], s[14:15], v[126:127] op_sel_hi:[1,0,1]
	v_add_f32_e32 v92, v122, v92
	v_add_f32_e32 v92, v125, v92
	v_add_f32_e32 v92, v124, v92
	v_mov_b32_e32 v128, v123
	v_mov_b32_e32 v129, v125
	v_mov_b32_e32 v123, v124
	s_waitcnt lgkmcnt(0)
	s_nop 1
	v_add_f32_dpp v92, v92, v92 quad_perm:[1,0,3,2] row_mask:0xf bank_mask:0xf
	s_waitcnt lgkmcnt(0)
	s_nop 1
	v_add_f32_dpp v92, v92, v92 quad_perm:[2,3,0,1] row_mask:0xf bank_mask:0xf
	s_waitcnt lgkmcnt(0)
	s_nop 1
	v_add_f32_dpp v92, v92, v92 row_half_mirror row_mask:0xf bank_mask:0xf
	s_waitcnt lgkmcnt(0)
	s_nop 1
	v_add_f32_dpp v92, v92, v92 row_mirror row_mask:0xf bank_mask:0xf
	s_waitcnt lgkmcnt(0)
	v_mov_b32_e32 v93, v92
	s_nop 1
	v_permlane16_swap_b32_e32 v92, v93
	v_add_f32_e32 v92, v92, v93
	s_waitcnt lgkmcnt(0)
	v_mov_b32_e32 v93, v92
	s_nop 1
	v_permlane32_swap_b32_e32 v92, v93
	v_add_f32_e32 v92, v92, v93
	v_mul_f32_e32 v92, 0x3a800000, v92
	v_pk_add_f32 v[80:81], v[80:81], v[92:93] op_sel_hi:[1,0] neg_lo:[0,1] neg_hi:[0,1]
	v_pk_add_f32 v[82:83], v[82:83], v[92:93] op_sel_hi:[1,0] neg_lo:[0,1] neg_hi:[0,1]
	v_pk_mul_f32 v[94:95], v[80:81], v[80:81]
	v_pk_mul_f32 v[108:109], v[82:83], v[82:83]
	v_pk_add_f32 v[84:85], v[84:85], v[92:93] op_sel_hi:[1,0] neg_lo:[0,1] neg_hi:[0,1]
	v_add_f32_e32 v94, v94, v108
	v_add_f32_e32 v94, v95, v94
	v_pk_mul_f32 v[116:117], v[84:85], v[84:85]
	v_pk_add_f32 v[86:87], v[86:87], v[92:93] op_sel_hi:[1,0] neg_lo:[0,1] neg_hi:[0,1]
	v_add_f32_e32 v94, v109, v94
	v_pk_mul_f32 v[118:119], v[86:87], v[86:87]
	v_add_f32_e32 v94, v116, v94
	v_add_f32_e32 v94, v118, v94
	v_pk_add_f32 v[88:89], v[88:89], v[92:93] op_sel_hi:[1,0] neg_lo:[0,1] neg_hi:[0,1]
	v_add_f32_e32 v94, v117, v94
	v_pk_mul_f32 v[120:121], v[88:89], v[88:89]
	v_pk_add_f32 v[90:91], v[90:91], v[92:93] op_sel_hi:[1,0] neg_lo:[0,1] neg_hi:[0,1]
	v_add_f32_e32 v94, v119, v94
	v_pk_mul_f32 v[126:127], v[90:91], v[90:91]
	v_add_f32_e32 v94, v120, v94
	v_pk_add_f32 v[128:129], v[128:129], v[92:93] op_sel_hi:[1,0] neg_lo:[0,1] neg_hi:[0,1]
	v_pk_add_f32 v[92:93], v[122:123], v[92:93] op_sel_hi:[1,0] neg_lo:[0,1] neg_hi:[0,1]
	v_add_f32_e32 v94, v126, v94
	v_mov_b32_e32 v122, v92
	v_mov_b32_e32 v123, v128
	v_add_f32_e32 v94, v121, v94
	v_pk_mul_f32 v[122:123], v[122:123], v[122:123]
	v_add_f32_e32 v94, v127, v94
	v_mov_b32_e32 v124, v93
	v_mov_b32_e32 v125, v129
	v_add_f32_e32 v94, v123, v94
	v_pk_mul_f32 v[124:125], v[124:125], v[124:125]
	v_add_f32_e32 v94, v122, v94
	v_add_f32_e32 v94, v125, v94
	v_add_f32_e32 v94, v124, v94
	s_waitcnt lgkmcnt(0)
	s_nop 1
	v_add_f32_dpp v94, v94, v94 quad_perm:[1,0,3,2] row_mask:0xf bank_mask:0xf
	s_waitcnt lgkmcnt(0)
	s_nop 1
	v_add_f32_dpp v94, v94, v94 quad_perm:[2,3,0,1] row_mask:0xf bank_mask:0xf
	s_waitcnt lgkmcnt(0)
	s_nop 1
	v_add_f32_dpp v94, v94, v94 row_half_mirror row_mask:0xf bank_mask:0xf
	s_waitcnt lgkmcnt(0)
	s_nop 1
	v_add_f32_dpp v94, v94, v94 row_mirror row_mask:0xf bank_mask:0xf
	s_waitcnt lgkmcnt(0)
	v_mov_b32_e32 v95, v94
	s_nop 1
	v_permlane16_swap_b32_e32 v94, v95
	v_add_f32_e32 v94, v94, v95
	s_waitcnt lgkmcnt(0)
; __device__ __forceinline__ void phase_ln(bf16* X, const bf16* Mx, const float* g, const float* b, int tid) {
;     ...
;         for (int u = 0; u < 4; ++u) { const int t = t0 + u * NGW; if (t < T) {
;             float x[16], m[16];
;             unpack8(xa[u][0], x); unpack8(xa[u][1], x + 8); unpack8(ma[u][0], m); unpack8(ma[u][1], m + 8);
;             float sum = 0.f;
; #pragma unroll
;             for (int i = 0; i < 16; ++i) { x[i] = ALPHA * x[i] + m[i]; sum += x[i]; }
;             const float mean = wave_sum(sum) * (1.f / DM);
;             float q = 0.f;
; #pragma unroll
;             for (int i = 0; i < 16; ++i) { x[i] -= mean; q += x[i] * x[i]; }
;             const float rstd = rsqrtf(wave_sum(q) * (1.f / DM) + LN_EPS);
; #pragma unroll
;             for (int i = 0; i < 16; ++i) x[i] = x[i] * rstd * gg[i] + bb[i];
;             store_row_bf16(X + (size_t)t * DM, lane, x); } }
	v_mov_b32_e32 v95, v94
	s_nop 1
	v_permlane32_swap_b32_e32 v94, v95
	v_add_f32_e32 v94, v94, v95
	v_fmamk_f32 v94, v94, 0x3a800000, v164
	v_mul_f32_e32 v95, 0x4b800000, v94
	v_cmp_gt_f32_e64 s[40:41], s9, v94
	s_nop 1
	v_cndmask_b32_e64 v94, v94, v95, s[40:41]
	v_rsq_f32_e32 v103, v94
	v_lshlrev_b64 v[94:95], 11, v[106:107]
	v_lshl_add_u64 v[94:95], v[4:5], 0, v[94:95]
	v_mul_f32_e32 v106, 0x45800000, v103
	v_cndmask_b32_e64 v106, v103, v106, s[40:41]
	v_pk_mul_f32 v[82:83], v[82:83], v[106:107] op_sel_hi:[1,0]
	v_pk_mul_f32 v[86:87], v[86:87], v[106:107] op_sel_hi:[1,0]
	v_pk_mul_f32 v[80:81], v[80:81], v[106:107] op_sel_hi:[1,0]
	v_pk_fma_f32 v[82:83], v[98:99], v[82:83], v[96:97]
	v_pk_mul_f32 v[84:85], v[84:85], v[106:107] op_sel_hi:[1,0]
	v_pk_fma_f32 v[86:87], v[100:101], v[86:87], v[16:17]
	v_pk_fma_f32 v[80:81], v[30:31], v[80:81], v[14:15]
	v_pk_fma_f32 v[84:85], v[26:27], v[84:85], v[10:11]
	v_pk_mul_f32 v[88:89], v[88:89], v[106:107] op_sel_hi:[1,0]
	v_pk_mul_f32 v[90:91], v[90:91], v[106:107] op_sel_hi:[1,0]
	v_pk_mul_f32 v[108:109], v[128:129], v[106:107] op_sel_hi:[1,0]
	v_pk_mul_f32 v[92:93], v[92:93], v[106:107] op_sel_hi:[1,0]
	v_bfe_u32 v103, v87, 16, 1
	v_bfe_u32 v106, v86, 16, 1
	v_bfe_u32 v107, v83, 16, 1
	v_bfe_u32 v115, v82, 16, 1
	v_add3_u32 v115, v82, v115, s84
	v_add3_u32 v107, v83, v107, s84
	v_add3_u32 v82, v86, v106, s84
	v_add3_u32 v83, v87, v103, s84
	v_bfe_u32 v86, v80, 16, 1
	v_bfe_u32 v87, v81, 16, 1
	v_bfe_u32 v103, v84, 16, 1
	v_bfe_u32 v106, v85, 16, 1
	v_add3_u32 v85, v85, v106, s84
	v_add3_u32 v84, v84, v103, s84
	v_add3_u32 v81, v81, v87, s84
	v_add3_u32 v80, v80, v86, s84
	v_lshrrev_b32_e32 v80, 16, v80
	v_lshrrev_b32_e32 v81, 16, v81
	v_lshrrev_b32_e32 v84, 16, v84
	v_lshrrev_b32_e32 v85, 16, v85
	v_pk_fma_f32 v[90:91], v[28:29], v[90:91], v[12:13]
	v_and_or_b32 v83, v83, s3, v85
	v_and_or_b32 v82, v82, s3, v84
	v_and_or_b32 v81, v107, s3, v81
	v_and_or_b32 v80, v115, s3, v80
	v_pk_fma_f32 v[88:89], v[22:23], v[88:89], v[6:7]
	v_pk_fma_f32 v[108:109], v[18:19], v[108:109], v[2:3]
	global_store_dwordx4 v[94:95], v[80:83], off
	v_pk_fma_f32 v[92:93], v[24:25], v[92:93], v[8:9]
	v_bfe_u32 v86, v108, 16, 1
	v_bfe_u32 v82, v91, 16, 1
	v_bfe_u32 v83, v90, 16, 1
	v_add3_u32 v84, v90, v83, s84
	v_add3_u32 v85, v91, v82, s84
	v_bfe_u32 v82, v88, 16, 1
	v_bfe_u32 v83, v89, 16, 1
	v_bfe_u32 v87, v109, 16, 1
	v_bfe_u32 v80, v93, 16, 1
	v_bfe_u32 v81, v92, 16, 1
	v_add3_u32 v87, v109, v87, s84
	v_add3_u32 v86, v108, v86, s84
	v_add3_u32 v83, v89, v83, s84
	v_add3_u32 v82, v88, v82, s84
	v_add3_u32 v81, v92, v81, s84
	v_add3_u32 v80, v93, v80, s84
	v_lshrrev_b32_e32 v88, 16, v82
	v_lshrrev_b32_e32 v89, 16, v83
	v_lshrrev_b32_e32 v82, 16, v86
	v_lshrrev_b32_e32 v83, 16, v87
	v_and_or_b32 v83, v80, s3, v83
	v_and_or_b32 v82, v81, s3, v82
	v_and_or_b32 v81, v85, s3, v89
	v_and_or_b32 v80, v84, s3, v88
	global_store_dwordx4 v[94:95], v[80:83], off offset:1024
	s_or_b64 exec, exec, s[36:37]
	s_and_saveexec_b64 s[36:37], vcc
	s_cbranch_execz .LBB0_152
.LBB0_164:
	v_lshlrev_b32_e32 v81, 16, v37
	v_lshlrev_b32_e32 v80, 16, v36
	v_lshlrev_b32_e32 v92, 16, v60
	v_lshlrev_b32_e32 v93, 16, v61
	v_and_b32_e32 v83, 0xffff0000, v37
	v_and_b32_e32 v82, 0xffff0000, v36
	v_and_b32_e32 v94, 0xffff0000, v60
	v_and_b32_e32 v95, 0xffff0000, v61
	v_pk_fma_f32 v[80:81], v[80:81], s[14:15], v[92:93] op_sel_hi:[1,0,1]
	v_pk_fma_f32 v[82:83], v[82:83], s[14:15], v[94:95] op_sel_hi:[1,0,1]
	v_add_f32_e32 v92, 0, v80
	v_add_f32_e32 v92, v82, v92
	v_lshlrev_b32_e32 v85, 16, v39
	v_lshlrev_b32_e32 v84, 16, v38
	v_lshlrev_b32_e32 v106, 16, v62
	v_lshlrev_b32_e32 v107, 16, v63
	v_add_f32_e32 v92, v81, v92
	v_and_b32_e32 v87, 0xffff0000, v39
	v_and_b32_e32 v86, 0xffff0000, v38
	v_and_b32_e32 v108, 0xffff0000, v62
	v_and_b32_e32 v109, 0xffff0000, v63
	v_add_f32_e32 v92, v83, v92
	v_pk_fma_f32 v[84:85], v[84:85], s[14:15], v[106:107] op_sel_hi:[1,0,1]
	v_pk_fma_f32 v[86:87], v[86:87], s[14:15], v[108:109] op_sel_hi:[1,0,1]
	v_add_f32_e32 v92, v84, v92
	v_add_f32_e32 v92, v86, v92
	v_lshlrev_b32_e32 v89, 16, v33
	v_lshlrev_b32_e32 v88, 16, v32
	v_lshlrev_b32_e32 v116, 16, v56
	v_lshlrev_b32_e32 v117, 16, v57
	v_add_f32_e32 v92, v85, v92
	v_and_b32_e32 v91, 0xffff0000, v33
	v_and_b32_e32 v90, 0xffff0000, v32
	v_and_b32_e32 v118, 0xffff0000, v56
	v_and_b32_e32 v119, 0xffff0000, v57
	v_add_f32_e32 v92, v87, v92
	v_pk_fma_f32 v[88:89], v[88:89], s[14:15], v[116:117] op_sel_hi:[1,0,1]
	v_pk_fma_f32 v[90:91], v[90:91], s[14:15], v[118:119] op_sel_hi:[1,0,1]
	v_add_f32_e32 v92, v88, v92
	v_add_f32_e32 v92, v90, v92
	v_and_b32_e32 v120, 0xffff0000, v34
	v_lshlrev_b32_e32 v121, 16, v34
	v_and_b32_e32 v122, 0xffff0000, v58
	v_lshlrev_b32_e32 v123, 16, v58
	v_add_f32_e32 v92, v89, v92
	v_pk_fma_f32 v[120:121], v[120:121], s[14:15], v[122:123] op_sel_hi:[1,0,1]
	v_add_f32_e32 v92, v91, v92
	v_and_b32_e32 v122, 0xffff0000, v35
	v_lshlrev_b32_e32 v123, 16, v35
	v_and_b32_e32 v124, 0xffff0000, v59
	v_lshlrev_b32_e32 v125, 16, v59
	v_add_f32_e32 v92, v121, v92
	v_pk_fma_f32 v[122:123], v[122:123], s[14:15], v[124:125] op_sel_hi:[1,0,1]
	v_add_f32_e32 v92, v120, v92
	v_add_f32_e32 v92, v123, v92
	v_add_f32_e32 v92, v122, v92
	v_mov_b32_e32 v126, v121
	v_mov_b32_e32 v127, v123
	v_mov_b32_e32 v121, v122
	s_waitcnt lgkmcnt(0)
	s_nop 1
	v_add_f32_dpp v92, v92, v92 quad_perm:[1,0,3,2] row_mask:0xf bank_mask:0xf
	s_waitcnt lgkmcnt(0)
	s_nop 1
	v_add_f32_dpp v92, v92, v92 quad_perm:[2,3,0,1] row_mask:0xf bank_mask:0xf
	s_waitcnt lgkmcnt(0)
; __device__ __forceinline__ void phase_ln(bf16* X, const bf16* Mx, const float* g, const float* b, int tid) {
;     ...
;         for (int u = 0; u < 4; ++u) { const int t = t0 + u * NGW; if (t < T) {
;             float x[16], m[16];
;             unpack8(xa[u][0], x); unpack8(xa[u][1], x + 8); unpack8(ma[u][0], m); unpack8(ma[u][1], m + 8);
;             float sum = 0.f;
; #pragma unroll
;             for (int i = 0; i < 16; ++i) { x[i] = ALPHA * x[i] + m[i]; sum += x[i]; }
;             const float mean = wave_sum(sum) * (1.f / DM);
;             float q = 0.f;
; #pragma unroll
;             for (int i = 0; i < 16; ++i) { x[i] -= mean; q += x[i] * x[i]; }
;             const float rstd = rsqrtf(wave_sum(q) * (1.f / DM) + LN_EPS);
; #pragma unroll
;             for (int i = 0; i < 16; ++i) x[i] = x[i] * rstd * gg[i] + bb[i];
;             store_row_bf16(X + (size_t)t * DM, lane, x); } }
	s_nop 1
	v_add_f32_dpp v92, v92, v92 row_half_mirror row_mask:0xf bank_mask:0xf
	s_waitcnt lgkmcnt(0)
	s_nop 1
	v_add_f32_dpp v92, v92, v92 row_mirror row_mask:0xf bank_mask:0xf
	s_waitcnt lgkmcnt(0)
	v_mov_b32_e32 v93, v92
	s_nop 1
	v_permlane16_swap_b32_e32 v92, v93
	v_add_f32_e32 v92, v92, v93
	s_waitcnt lgkmcnt(0)
	v_mov_b32_e32 v93, v92
	s_nop 1
	v_permlane32_swap_b32_e32 v92, v93
	v_add_f32_e32 v92, v92, v93
	v_mul_f32_e32 v92, 0x3a800000, v92
	v_pk_add_f32 v[80:81], v[80:81], v[92:93] op_sel_hi:[1,0] neg_lo:[0,1] neg_hi:[0,1]
	v_pk_add_f32 v[82:83], v[82:83], v[92:93] op_sel_hi:[1,0] neg_lo:[0,1] neg_hi:[0,1]
	v_pk_mul_f32 v[94:95], v[80:81], v[80:81]
	v_pk_mul_f32 v[106:107], v[82:83], v[82:83]
	v_pk_add_f32 v[84:85], v[84:85], v[92:93] op_sel_hi:[1,0] neg_lo:[0,1] neg_hi:[0,1]
	v_add_f32_e32 v94, v94, v106
	v_add_f32_e32 v94, v95, v94
	v_pk_mul_f32 v[108:109], v[84:85], v[84:85]
	v_pk_add_f32 v[86:87], v[86:87], v[92:93] op_sel_hi:[1,0] neg_lo:[0,1] neg_hi:[0,1]
	v_add_f32_e32 v94, v107, v94
	v_pk_mul_f32 v[116:117], v[86:87], v[86:87]
	v_add_f32_e32 v94, v108, v94
	v_add_f32_e32 v94, v116, v94
	v_pk_add_f32 v[88:89], v[88:89], v[92:93] op_sel_hi:[1,0] neg_lo:[0,1] neg_hi:[0,1]
	v_add_f32_e32 v94, v109, v94
	v_pk_mul_f32 v[118:119], v[88:89], v[88:89]
	v_pk_add_f32 v[90:91], v[90:91], v[92:93] op_sel_hi:[1,0] neg_lo:[0,1] neg_hi:[0,1]
	v_add_f32_e32 v94, v117, v94
	v_pk_mul_f32 v[124:125], v[90:91], v[90:91]
	v_add_f32_e32 v94, v118, v94
	v_pk_add_f32 v[126:127], v[126:127], v[92:93] op_sel_hi:[1,0] neg_lo:[0,1] neg_hi:[0,1]
	v_pk_add_f32 v[92:93], v[120:121], v[92:93] op_sel_hi:[1,0] neg_lo:[0,1] neg_hi:[0,1]
	v_add_f32_e32 v94, v124, v94
	v_mov_b32_e32 v120, v92
	v_mov_b32_e32 v121, v126
	v_add_f32_e32 v94, v119, v94
	v_pk_mul_f32 v[120:121], v[120:121], v[120:121]
	v_add_f32_e32 v94, v125, v94
	v_mov_b32_e32 v122, v93
	v_mov_b32_e32 v123, v127
	v_add_f32_e32 v94, v121, v94
	v_pk_mul_f32 v[122:123], v[122:123], v[122:123]
	v_add_f32_e32 v94, v120, v94
	v_add_f32_e32 v94, v123, v94
	v_add_f32_e32 v94, v122, v94
	s_waitcnt lgkmcnt(0)
	s_nop 1
	v_add_f32_dpp v94, v94, v94 quad_perm:[1,0,3,2] row_mask:0xf bank_mask:0xf
	s_waitcnt lgkmcnt(0)
	s_nop 1
	v_add_f32_dpp v94, v94, v94 quad_perm:[2,3,0,1] row_mask:0xf bank_mask:0xf
	s_waitcnt lgkmcnt(0)
	s_nop 1
	v_add_f32_dpp v94, v94, v94 row_half_mirror row_mask:0xf bank_mask:0xf
	s_waitcnt lgkmcnt(0)
	s_nop 1
	v_add_f32_dpp v94, v94, v94 row_mirror row_mask:0xf bank_mask:0xf
	s_waitcnt lgkmcnt(0)
	v_mov_b32_e32 v95, v94
	s_nop 1
	v_permlane16_swap_b32_e32 v94, v95
	v_add_f32_e32 v94, v94, v95
	s_waitcnt lgkmcnt(0)
	v_mov_b32_e32 v95, v94
	s_nop 1
	v_permlane32_swap_b32_e32 v94, v95
	v_add_f32_e32 v94, v94, v95
	v_fmamk_f32 v94, v94, 0x3a800000, v164
	v_mul_f32_e32 v95, 0x4b800000, v94
	v_cmp_gt_f32_e32 vcc, s9, v94
	s_nop 1
	v_cndmask_b32_e32 v94, v94, v95, vcc
	v_rsq_f32_e32 v103, v94
	v_lshlrev_b64 v[94:95], 11, v[104:105]
	v_lshl_add_u64 v[94:95], v[4:5], 0, v[94:95]
	v_mul_f32_e32 v104, 0x45800000, v103
	v_cndmask_b32_e32 v104, v103, v104, vcc
	v_pk_mul_f32 v[82:83], v[82:83], v[104:105] op_sel_hi:[1,0]
	v_pk_mul_f32 v[86:87], v[86:87], v[104:105] op_sel_hi:[1,0]
	v_pk_mul_f32 v[80:81], v[80:81], v[104:105] op_sel_hi:[1,0]
	v_pk_fma_f32 v[82:83], v[98:99], v[82:83], v[96:97]
	v_pk_mul_f32 v[84:85], v[84:85], v[104:105] op_sel_hi:[1,0]
	v_pk_fma_f32 v[86:87], v[100:101], v[86:87], v[16:17]
	v_pk_fma_f32 v[80:81], v[30:31], v[80:81], v[14:15]
	v_pk_fma_f32 v[84:85], v[26:27], v[84:85], v[10:11]
	v_pk_mul_f32 v[88:89], v[88:89], v[104:105] op_sel_hi:[1,0]
	v_pk_mul_f32 v[90:91], v[90:91], v[104:105] op_sel_hi:[1,0]
	v_pk_mul_f32 v[106:107], v[126:127], v[104:105] op_sel_hi:[1,0]
	v_pk_mul_f32 v[92:93], v[92:93], v[104:105] op_sel_hi:[1,0]
	v_bfe_u32 v103, v87, 16, 1
	v_bfe_u32 v104, v86, 16, 1
	v_bfe_u32 v105, v83, 16, 1
	v_bfe_u32 v108, v82, 16, 1
	v_add3_u32 v108, v82, v108, s84
	v_add3_u32 v105, v83, v105, s84
	v_add3_u32 v82, v86, v104, s84
	v_add3_u32 v83, v87, v103, s84
	v_bfe_u32 v86, v80, 16, 1
	v_bfe_u32 v87, v81, 16, 1
	v_bfe_u32 v103, v84, 16, 1
	v_bfe_u32 v104, v85, 16, 1
	v_add3_u32 v85, v85, v104, s84
	v_add3_u32 v84, v84, v103, s84
	v_add3_u32 v81, v81, v87, s84
	v_add3_u32 v80, v80, v86, s84
	v_lshrrev_b32_e32 v80, 16, v80
	v_lshrrev_b32_e32 v81, 16, v81
	v_lshrrev_b32_e32 v84, 16, v84
	v_lshrrev_b32_e32 v85, 16, v85
	v_pk_fma_f32 v[90:91], v[28:29], v[90:91], v[12:13]
	v_and_or_b32 v83, v83, s3, v85
	v_and_or_b32 v82, v82, s3, v84
	v_and_or_b32 v81, v105, s3, v81
	v_and_or_b32 v80, v108, s3, v80
	v_pk_fma_f32 v[88:89], v[22:23], v[88:89], v[6:7]
	v_pk_fma_f32 v[106:107], v[18:19], v[106:107], v[2:3]
	global_store_dwordx4 v[94:95], v[80:83], off
	v_pk_fma_f32 v[92:93], v[24:25], v[92:93], v[8:9]
	v_bfe_u32 v86, v106, 16, 1
	v_bfe_u32 v82, v91, 16, 1
	v_bfe_u32 v83, v90, 16, 1
	v_add3_u32 v84, v90, v83, s84
	v_add3_u32 v85, v91, v82, s84
	v_bfe_u32 v82, v88, 16, 1
	v_bfe_u32 v83, v89, 16, 1
	v_bfe_u32 v87, v107, 16, 1
	v_bfe_u32 v80, v93, 16, 1
	v_bfe_u32 v81, v92, 16, 1
	v_add3_u32 v87, v107, v87, s84
	v_add3_u32 v86, v106, v86, s84
	v_add3_u32 v83, v89, v83, s84
	v_add3_u32 v82, v88, v82, s84
	v_add3_u32 v81, v92, v81, s84
	v_add3_u32 v80, v93, v80, s84
	v_lshrrev_b32_e32 v88, 16, v82
	v_lshrrev_b32_e32 v89, 16, v83
	v_lshrrev_b32_e32 v82, 16, v86
	v_lshrrev_b32_e32 v83, 16, v87
	v_and_or_b32 v83, v80, s3, v83
	v_and_or_b32 v82, v81, s3, v82
	v_and_or_b32 v81, v85, s3, v89
	v_and_or_b32 v80, v84, s3, v88
	global_store_dwordx4 v[94:95], v[80:83], off offset:1024
	s_branch .LBB0_152

; __device__ __forceinline__ u32x4 pack8(const float* f) { u32x4 o; o.x = pk2(f[0], f[1]); o.y = pk2(f[2], f[3]); o.z = pk2(f[4], f[5]); o.w = pk2(f[6], f[7]); return o; }
; __device__ __forceinline__ void phase_norm(bf16* Y, const float* g, int tid) {
;     ...
;         for (int u = 0; u < 4; ++u) { const int t = t0 + u * NGW; if (t < T) {
;             bf16* row = Y + (size_t)t * DM + lane * 16;
;             float y[16];
;             unpack8(ya[u][0], y); unpack8(ya[u][1], y + 8);
;             float ss = 0.f;
; #pragma unroll
;             for (int i = 0; i < 16; ++i) ss += y[i] * y[i];
;             ss += __shfl_xor(ss, 1); ss += __shfl_xor(ss, 2); ss += __shfl_xor(ss, 4); ss += __shfl_xor(ss, 8);
;             const float r = rsqrtf(ss * (1.f / 256.f) + 1e-6f);
; #pragma unroll
;             for (int i = 0; i < 16; ++i) y[i] = y[i] * r * gg[i];
;             *(u32x4*)row = pack8(y); *(u32x4*)(row + 8) = pack8(y + 8); } }
.LBB0_176:
	s_or_b64 exec, exec, s[36:37]
	s_waitcnt vmcnt(0)
	v_lshlrev_b32_e32 v71, 16, v45
	v_lshlrev_b32_e32 v70, 16, v44
	v_and_b32_e32 v45, 0xffff0000, v45
	v_and_b32_e32 v44, 0xffff0000, v44
	v_pk_mul_f32 v[72:73], v[70:71], v[70:71]
	v_pk_mul_f32 v[74:75], v[44:45], v[44:45]
	v_lshlrev_b32_e32 v77, 16, v47
	v_add_f32_e32 v63, v72, v74
	v_lshlrev_b32_e32 v76, 16, v46
	v_add_f32_e32 v63, v73, v63
	v_and_b32_e32 v47, 0xffff0000, v47
	v_and_b32_e32 v46, 0xffff0000, v46
	v_pk_mul_f32 v[78:79], v[76:77], v[76:77]
	v_add_f32_e32 v63, v75, v63
	v_pk_mul_f32 v[80:81], v[46:47], v[46:47]
	v_add_f32_e32 v63, v78, v63
	v_add_f32_e32 v63, v80, v63
	v_add_f32_e32 v63, v79, v63
	v_lshlrev_b32_e32 v83, 16, v41
	v_lshlrev_b32_e32 v82, 16, v40
	v_and_b32_e32 v41, 0xffff0000, v41
	v_add_f32_e32 v63, v81, v63
	v_and_b32_e32 v40, 0xffff0000, v40
	v_mov_b32_e32 v84, v41
	v_mov_b32_e32 v85, v83
	v_fmac_f32_e32 v63, v82, v82
	v_pk_mul_f32 v[84:85], v[84:85], v[84:85]
	v_fmac_f32_e32 v63, v40, v40
	v_and_b32_e32 v64, 0xffff0000, v42
	v_lshlrev_b32_e32 v65, 16, v42
	v_add_f32_e32 v63, v85, v63
	v_pk_mul_f32 v[66:67], v[64:65], v[64:65]
	v_add_f32_e32 v63, v84, v63
	v_and_b32_e32 v68, 0xffff0000, v43
	v_lshlrev_b32_e32 v69, 16, v43
	v_add_f32_e32 v63, v67, v63
	v_pk_mul_f32 v[42:43], v[68:69], v[68:69]
	v_add_f32_e32 v63, v66, v63
	v_add_f32_e32 v43, v43, v63
	v_add_f32_e32 v42, v42, v43
	s_mov_b32 s9, 0x800000
	s_waitcnt lgkmcnt(0)
	s_nop 1
	v_add_f32_dpp v42, v42, v42 quad_perm:[1,0,3,2] row_mask:0xf bank_mask:0xf
	s_waitcnt lgkmcnt(0)
	s_nop 1
	v_add_f32_dpp v42, v42, v42 quad_perm:[2,3,0,1] row_mask:0xf bank_mask:0xf
	s_waitcnt lgkmcnt(0)
	s_nop 1
	v_add_f32_dpp v42, v42, v42 row_half_mirror row_mask:0xf bank_mask:0xf
	s_waitcnt lgkmcnt(0)
	s_nop 1
	v_add_f32_dpp v42, v42, v42 row_mirror row_mask:0xf bank_mask:0xf
	v_fmamk_f32 v42, v42, 0x3b800000, v165
	v_mul_f32_e32 v43, 0x4b800000, v42
	v_cmp_gt_f32_e64 s[44:45], s9, v42
	s_nop 1
	v_cndmask_b32_e64 v42, v42, v43, s[44:45]
	v_rsq_f32_e32 v42, v42
	s_nop 0
	v_mul_f32_e32 v43, 0x45800000, v42
	v_cndmask_b32_e64 v66, v42, v43, s[44:45]
	v_pk_mul_f32 v[44:45], v[66:67], v[44:45] op_sel_hi:[0,1]
	v_pk_mul_f32 v[46:47], v[66:67], v[46:47] op_sel_hi:[0,1]
	v_pk_mul_f32 v[42:43], v[66:67], v[70:71] op_sel_hi:[0,1]
	v_pk_mul_f32 v[44:45], v[50:51], v[44:45]
	v_pk_mul_f32 v[70:71], v[66:67], v[76:77] op_sel_hi:[0,1]
	v_pk_mul_f32 v[46:47], v[4:5], v[46:47]
	v_pk_mul_f32 v[40:41], v[66:67], v[40:41] op_sel_hi:[0,1]
	v_pk_mul_f32 v[42:43], v[2:3], v[42:43]
	v_pk_mul_f32 v[70:71], v[6:7], v[70:71]
	v_pk_mul_f32 v[72:73], v[66:67], v[82:83] op_sel_hi:[0,1]
	v_pk_mul_f32 v[74:75], v[8:9], v[40:41]
	v_bfe_u32 v40, v47, 16, 1
	v_bfe_u32 v41, v46, 16, 1
	v_bfe_u32 v63, v45, 16, 1
	v_bfe_u32 v67, v44, 16, 1
	v_add3_u32 v44, v44, v67, s84
	v_add3_u32 v45, v45, v63, s84
	v_add3_u32 v41, v46, v41, s84
	v_add3_u32 v40, v47, v40, s84
	v_bfe_u32 v46, v42, 16, 1
	v_bfe_u32 v47, v43, 16, 1
	v_bfe_u32 v63, v70, 16, 1
	v_bfe_u32 v67, v71, 16, 1
	v_add3_u32 v67, v71, v67, s84
	v_add3_u32 v63, v70, v63, s84
	v_add3_u32 v43, v43, v47, s84
	v_add3_u32 v42, v42, v46, s84
	v_lshrrev_b32_e32 v46, 16, v42
	v_lshrrev_b32_e32 v47, 16, v43
	v_lshrrev_b32_e32 v42, 16, v63
	v_lshrrev_b32_e32 v43, 16, v67
	v_and_or_b32 v43, v40, s3, v43
	v_and_or_b32 v42, v41, s3, v42
	v_and_or_b32 v41, v45, s3, v47
	v_and_or_b32 v40, v44, s3, v46
	global_store_dwordx4 v[58:59], v[40:43], off
	v_pk_mul_f32 v[72:73], v[10:11], v[72:73]
	v_bfe_u32 v46, v75, 16, 1
	v_mov_b32_e32 v40, v65
	v_mov_b32_e32 v65, v68
	v_mov_b32_e32 v41, v69
	v_pk_mul_f32 v[42:43], v[66:67], v[64:65] op_sel_hi:[0,1]
	v_pk_mul_f32 v[40:41], v[66:67], v[40:41] op_sel_hi:[0,1]
	v_pk_mul_f32 v[42:43], v[12:13], v[42:43]
	v_pk_mul_f32 v[40:41], v[14:15], v[40:41]
	v_bfe_u32 v44, v43, 16, 1
	v_bfe_u32 v45, v42, 16, 1
	v_add3_u32 v42, v42, v45, s84
	v_add3_u32 v43, v43, v44, s84
	v_bfe_u32 v44, v72, 16, 1
	v_bfe_u32 v45, v73, 16, 1
	v_bfe_u32 v63, v40, 16, 1
	v_bfe_u32 v64, v41, 16, 1
	v_bfe_u32 v47, v74, 16, 1
	v_add3_u32 v41, v41, v64, s84
	v_add3_u32 v40, v40, v63, s84
	v_add3_u32 v45, v73, v45, s84
	v_add3_u32 v44, v72, v44, s84
	v_add3_u32 v47, v74, v47, s84
	v_add3_u32 v46, v75, v46, s84
	v_lshrrev_b32_e32 v44, 16, v44
	v_lshrrev_b32_e32 v45, 16, v45
	v_lshrrev_b32_e32 v40, 16, v40
	v_lshrrev_b32_e32 v41, 16, v41
	v_and_or_b32 v43, v43, s3, v41
	v_and_or_b32 v42, v42, s3, v40
	v_and_or_b32 v41, v46, s3, v45
	v_and_or_b32 v40, v47, s3, v44
	global_store_dwordx4 v[58:59], v[40:43], off offset:16
	s_and_saveexec_b64 s[36:37], s[42:43]
	s_cbranch_execz .LBB0_179
; __device__ __forceinline__ u32x4 pack8(const float* f) { u32x4 o; o.x = pk2(f[0], f[1]); o.y = pk2(f[2], f[3]); o.z = pk2(f[4], f[5]); o.w = pk2(f[6], f[7]); return o; }
; __device__ __forceinline__ void phase_norm(bf16* Y, const float* g, int tid) {
;     ...
;         for (int u = 0; u < 4; ++u) { const int t = t0 + u * NGW; if (t < T) {
;             bf16* row = Y + (size_t)t * DM + lane * 16;
;             float y[16];
;             unpack8(ya[u][0], y); unpack8(ya[u][1], y + 8);
;             float ss = 0.f;
; #pragma unroll
;             for (int i = 0; i < 16; ++i) ss += y[i] * y[i];
;             ss += __shfl_xor(ss, 1); ss += __shfl_xor(ss, 2); ss += __shfl_xor(ss, 4); ss += __shfl_xor(ss, 8);
;             const float r = rsqrtf(ss * (1.f / 256.f) + 1e-6f);
; #pragma unroll
;             for (int i = 0; i < 16; ++i) y[i] = y[i] * r * gg[i];
;             *(u32x4*)row = pack8(y); *(u32x4*)(row + 8) = pack8(y + 8); } }
	v_lshlrev_b32_e32 v59, 16, v37
	v_lshlrev_b32_e32 v58, 16, v36
	v_and_b32_e32 v65, 0xffff0000, v37
	v_and_b32_e32 v64, 0xffff0000, v36
	v_pk_mul_f32 v[66:67], v[58:59], v[58:59]
	v_pk_mul_f32 v[68:69], v[64:65], v[64:65]
	v_lshlrev_b32_e32 v71, 16, v39
	v_add_f32_e32 v63, v66, v68
	v_lshlrev_b32_e32 v70, 16, v38
	v_add_f32_e32 v63, v67, v63
	v_and_b32_e32 v73, 0xffff0000, v39
	v_and_b32_e32 v72, 0xffff0000, v38
	v_pk_mul_f32 v[74:75], v[70:71], v[70:71]
	v_add_f32_e32 v63, v69, v63
	v_pk_mul_f32 v[76:77], v[72:73], v[72:73]
	v_add_f32_e32 v63, v74, v63
	v_add_f32_e32 v63, v76, v63
	v_add_f32_e32 v63, v75, v63
	v_lshlrev_b32_e32 v79, 16, v29
	v_lshlrev_b32_e32 v78, 16, v28
	v_and_b32_e32 v81, 0xffff0000, v29
	v_add_f32_e32 v63, v77, v63
	v_and_b32_e32 v80, 0xffff0000, v28
	v_mov_b32_e32 v82, v81
	v_mov_b32_e32 v83, v79
	v_fmac_f32_e32 v63, v78, v78
	v_pk_mul_f32 v[82:83], v[82:83], v[82:83]
	v_fmac_f32_e32 v63, v80, v80
	v_and_b32_e32 v44, 0xffff0000, v30
	v_lshlrev_b32_e32 v45, 16, v30
	v_add_f32_e32 v63, v83, v63
	v_pk_mul_f32 v[40:41], v[44:45], v[44:45]
	v_add_f32_e32 v63, v82, v63
	v_and_b32_e32 v46, 0xffff0000, v31
	v_lshlrev_b32_e32 v47, 16, v31
	v_add_f32_e32 v41, v41, v63
	v_pk_mul_f32 v[42:43], v[46:47], v[46:47]
	v_add_f32_e32 v40, v40, v41
	v_add_f32_e32 v40, v43, v40
	v_add_f32_e32 v40, v42, v40
	s_waitcnt lgkmcnt(0)
	s_nop 1
	v_add_f32_dpp v40, v40, v40 quad_perm:[1,0,3,2] row_mask:0xf bank_mask:0xf
	s_waitcnt lgkmcnt(0)
	s_nop 1
	v_add_f32_dpp v40, v40, v40 quad_perm:[2,3,0,1] row_mask:0xf bank_mask:0xf
	s_waitcnt lgkmcnt(0)
	s_nop 1
	v_add_f32_dpp v40, v40, v40 row_half_mirror row_mask:0xf bank_mask:0xf
	s_waitcnt lgkmcnt(0)
	s_nop 1
	v_add_f32_dpp v40, v40, v40 row_mirror row_mask:0xf bank_mask:0xf
	v_fmamk_f32 v40, v40, 0x3b800000, v165
	v_mul_f32_e32 v41, 0x4b800000, v40
	v_cmp_gt_f32_e64 s[42:43], s9, v40
	s_nop 1
	v_cndmask_b32_e64 v40, v40, v41, s[42:43]
	v_rsq_f32_e32 v42, v40
	v_lshlrev_b64 v[40:41], 11, v[52:53]
	v_lshl_add_u64 v[66:67], v[48:49], 0, v[40:41]
	v_mul_f32_e32 v40, 0x45800000, v42
	v_cndmask_b32_e64 v68, v42, v40, s[42:43]
	v_pk_mul_f32 v[42:43], v[68:69], v[64:65] op_sel_hi:[0,1]
	v_pk_mul_f32 v[64:65], v[68:69], v[72:73] op_sel_hi:[0,1]
	v_pk_mul_f32 v[40:41], v[68:69], v[58:59] op_sel_hi:[0,1]
	v_pk_mul_f32 v[42:43], v[50:51], v[42:43]
	v_pk_mul_f32 v[58:59], v[68:69], v[70:71] op_sel_hi:[0,1]
	v_pk_mul_f32 v[64:65], v[4:5], v[64:65]
	v_pk_mul_f32 v[40:41], v[2:3], v[40:41]
	v_pk_mul_f32 v[58:59], v[6:7], v[58:59]
	v_pk_mul_f32 v[70:71], v[68:69], v[78:79] op_sel_hi:[0,1]
	v_pk_mul_f32 v[72:73], v[68:69], v[80:81] op_sel_hi:[0,1]
	v_bfe_u32 v53, v65, 16, 1
	v_bfe_u32 v63, v64, 16, 1
	v_bfe_u32 v69, v43, 16, 1
	v_bfe_u32 v74, v42, 16, 1
	v_add3_u32 v74, v42, v74, s84
	v_add3_u32 v69, v43, v69, s84
	v_add3_u32 v42, v64, v63, s84
	v_add3_u32 v43, v65, v53, s84
	v_bfe_u32 v53, v40, 16, 1
	v_bfe_u32 v63, v41, 16, 1
	v_bfe_u32 v64, v58, 16, 1
	v_bfe_u32 v65, v59, 16, 1
	v_add3_u32 v59, v59, v65, s84
	v_add3_u32 v58, v58, v64, s84
	v_add3_u32 v41, v41, v63, s84
	v_add3_u32 v40, v40, v53, s84
	v_lshrrev_b32_e32 v40, 16, v40
	v_lshrrev_b32_e32 v41, 16, v41
	v_lshrrev_b32_e32 v53, 16, v58
	v_lshrrev_b32_e32 v58, 16, v59
	v_and_or_b32 v43, v43, s3, v58
	v_and_or_b32 v42, v42, s3, v53
	v_and_or_b32 v41, v69, s3, v41
	v_and_or_b32 v40, v74, s3, v40
	global_store_dwordx4 v[66:67], v[40:43], off
	v_pk_mul_f32 v[70:71], v[10:11], v[70:71]
	v_pk_mul_f32 v[72:73], v[8:9], v[72:73]
	v_mov_b32_e32 v40, v45
	v_mov_b32_e32 v45, v46
	v_mov_b32_e32 v41, v47
	v_pk_mul_f32 v[42:43], v[68:69], v[44:45] op_sel_hi:[0,1]
	v_pk_mul_f32 v[40:41], v[68:69], v[40:41] op_sel_hi:[0,1]
	v_pk_mul_f32 v[42:43], v[12:13], v[42:43]
	v_pk_mul_f32 v[40:41], v[14:15], v[40:41]
	v_bfe_u32 v44, v43, 16, 1
	v_bfe_u32 v45, v42, 16, 1
	v_add3_u32 v42, v42, v45, s84
	v_add3_u32 v43, v43, v44, s84
	v_bfe_u32 v44, v70, 16, 1
	v_bfe_u32 v45, v71, 16, 1
	v_bfe_u32 v53, v40, 16, 1
	v_bfe_u32 v58, v41, 16, 1
	v_bfe_u32 v46, v73, 16, 1
	v_bfe_u32 v47, v72, 16, 1
	v_add3_u32 v41, v41, v58, s84
	v_add3_u32 v40, v40, v53, s84
	v_add3_u32 v45, v71, v45, s84
	v_add3_u32 v44, v70, v44, s84
	v_add3_u32 v47, v72, v47, s84
	v_add3_u32 v46, v73, v46, s84
	v_lshrrev_b32_e32 v44, 16, v44
	v_lshrrev_b32_e32 v45, 16, v45
	v_lshrrev_b32_e32 v40, 16, v40
	v_lshrrev_b32_e32 v41, 16, v41
	v_and_or_b32 v43, v43, s3, v41
	v_and_or_b32 v42, v42, s3, v40
	v_and_or_b32 v41, v46, s3, v45
	v_and_or_b32 v40, v47, s3, v44
	global_store_dwordx4 v[66:67], v[40:43], off offset:16
	s_or_b64 exec, exec, s[36:37]
	s_and_saveexec_b64 s[36:37], s[40:41]
	s_cbranch_execnz .LBB0_180

; __device__ __forceinline__ u32x4 pack8(const float* f) { u32x4 o; o.x = pk2(f[0], f[1]); o.y = pk2(f[2], f[3]); o.z = pk2(f[4], f[5]); o.w = pk2(f[6], f[7]); return o; }
; __device__ __forceinline__ void phase_norm(bf16* Y, const float* g, int tid) {
;     ...
;         for (int u = 0; u < 4; ++u) { const int t = t0 + u * NGW; if (t < T) {
;             bf16* row = Y + (size_t)t * DM + lane * 16;
;             float y[16];
;             unpack8(ya[u][0], y); unpack8(ya[u][1], y + 8);
;             float ss = 0.f;
; #pragma unroll
;             for (int i = 0; i < 16; ++i) ss += y[i] * y[i];
;             ss += __shfl_xor(ss, 1); ss += __shfl_xor(ss, 2); ss += __shfl_xor(ss, 4); ss += __shfl_xor(ss, 8);
;             const float r = rsqrtf(ss * (1.f / 256.f) + 1e-6f);
; #pragma unroll
;             for (int i = 0; i < 16; ++i) y[i] = y[i] * r * gg[i];
;             *(u32x4*)row = pack8(y); *(u32x4*)(row + 8) = pack8(y + 8); } }
.LBB0_180:
	v_lshlrev_b32_e32 v59, 16, v33
	v_lshlrev_b32_e32 v58, 16, v32
	v_and_b32_e32 v65, 0xffff0000, v33
	v_and_b32_e32 v64, 0xffff0000, v32
	v_pk_mul_f32 v[66:67], v[58:59], v[58:59]
	v_pk_mul_f32 v[68:69], v[64:65], v[64:65]
	v_lshlrev_b32_e32 v71, 16, v35
	v_add_f32_e32 v53, v66, v68
	v_lshlrev_b32_e32 v70, 16, v34
	v_add_f32_e32 v53, v67, v53
	v_and_b32_e32 v73, 0xffff0000, v35
	v_and_b32_e32 v72, 0xffff0000, v34
	v_pk_mul_f32 v[74:75], v[70:71], v[70:71]
	v_add_f32_e32 v53, v69, v53
	v_pk_mul_f32 v[76:77], v[72:73], v[72:73]
	v_add_f32_e32 v53, v74, v53
	v_add_f32_e32 v53, v76, v53
	v_add_f32_e32 v53, v75, v53
	v_lshlrev_b32_e32 v79, 16, v21
	v_lshlrev_b32_e32 v78, 16, v20
	v_and_b32_e32 v81, 0xffff0000, v21
	v_add_f32_e32 v53, v77, v53
	v_and_b32_e32 v80, 0xffff0000, v20
	v_mov_b32_e32 v82, v81
	v_mov_b32_e32 v83, v79
	v_fmac_f32_e32 v53, v78, v78
	v_pk_mul_f32 v[82:83], v[82:83], v[82:83]
	v_fmac_f32_e32 v53, v80, v80
	v_and_b32_e32 v44, 0xffff0000, v22
	v_lshlrev_b32_e32 v45, 16, v22
	v_add_f32_e32 v53, v83, v53
	v_pk_mul_f32 v[40:41], v[44:45], v[44:45]
	v_add_f32_e32 v53, v82, v53
	v_and_b32_e32 v46, 0xffff0000, v23
	v_lshlrev_b32_e32 v47, 16, v23
	v_add_f32_e32 v41, v41, v53
	v_pk_mul_f32 v[42:43], v[46:47], v[46:47]
	v_add_f32_e32 v40, v40, v41
	v_add_f32_e32 v40, v43, v40
	v_add_f32_e32 v40, v42, v40
	s_waitcnt lgkmcnt(0)
	s_nop 1
	v_add_f32_dpp v40, v40, v40 quad_perm:[1,0,3,2] row_mask:0xf bank_mask:0xf
	s_waitcnt lgkmcnt(0)
	s_nop 1
	v_add_f32_dpp v40, v40, v40 quad_perm:[2,3,0,1] row_mask:0xf bank_mask:0xf
	s_waitcnt lgkmcnt(0)
	s_nop 1
	v_add_f32_dpp v40, v40, v40 row_half_mirror row_mask:0xf bank_mask:0xf
	s_waitcnt lgkmcnt(0)
	s_nop 1
	v_add_f32_dpp v40, v40, v40 row_mirror row_mask:0xf bank_mask:0xf
	v_fmamk_f32 v40, v40, 0x3b800000, v165
	v_mul_f32_e32 v41, 0x4b800000, v40
	v_cmp_gt_f32_e64 s[40:41], s9, v40
	s_nop 1
	v_cndmask_b32_e64 v40, v40, v41, s[40:41]
	v_rsq_f32_e32 v42, v40
	v_lshlrev_b64 v[40:41], 11, v[56:57]
	v_lshl_add_u64 v[56:57], v[48:49], 0, v[40:41]
	v_mul_f32_e32 v40, 0x45800000, v42
	v_cndmask_b32_e64 v66, v42, v40, s[40:41]
	v_pk_mul_f32 v[42:43], v[66:67], v[64:65] op_sel_hi:[0,1]
	v_pk_mul_f32 v[64:65], v[66:67], v[72:73] op_sel_hi:[0,1]
	v_pk_mul_f32 v[40:41], v[66:67], v[58:59] op_sel_hi:[0,1]
	v_pk_mul_f32 v[42:43], v[50:51], v[42:43]
	v_pk_mul_f32 v[58:59], v[66:67], v[70:71] op_sel_hi:[0,1]
	v_pk_mul_f32 v[64:65], v[4:5], v[64:65]
	v_pk_mul_f32 v[40:41], v[2:3], v[40:41]
	v_pk_mul_f32 v[58:59], v[6:7], v[58:59]
	v_pk_mul_f32 v[68:69], v[66:67], v[78:79] op_sel_hi:[0,1]
	v_pk_mul_f32 v[70:71], v[66:67], v[80:81] op_sel_hi:[0,1]
	v_bfe_u32 v53, v65, 16, 1
	v_bfe_u32 v63, v64, 16, 1
	v_bfe_u32 v67, v43, 16, 1
	v_bfe_u32 v72, v42, 16, 1
	v_add3_u32 v72, v42, v72, s84
	v_add3_u32 v67, v43, v67, s84
	v_add3_u32 v42, v64, v63, s84
	v_add3_u32 v43, v65, v53, s84
	v_bfe_u32 v53, v40, 16, 1
	v_bfe_u32 v63, v41, 16, 1
	v_bfe_u32 v64, v58, 16, 1
	v_bfe_u32 v65, v59, 16, 1
	v_add3_u32 v59, v59, v65, s84
	v_add3_u32 v58, v58, v64, s84
	v_add3_u32 v41, v41, v63, s84
	v_add3_u32 v40, v40, v53, s84
	v_lshrrev_b32_e32 v40, 16, v40
	v_lshrrev_b32_e32 v41, 16, v41
	v_lshrrev_b32_e32 v53, 16, v58
	v_lshrrev_b32_e32 v58, 16, v59
	v_and_or_b32 v43, v43, s3, v58
	v_and_or_b32 v42, v42, s3, v53
	v_and_or_b32 v41, v67, s3, v41
	v_and_or_b32 v40, v72, s3, v40
	global_store_dwordx4 v[56:57], v[40:43], off
	v_pk_mul_f32 v[68:69], v[10:11], v[68:69]
	v_pk_mul_f32 v[70:71], v[8:9], v[70:71]
	v_mov_b32_e32 v40, v45
	v_mov_b32_e32 v45, v46
	v_mov_b32_e32 v41, v47
	v_pk_mul_f32 v[42:43], v[66:67], v[44:45] op_sel_hi:[0,1]
	v_pk_mul_f32 v[40:41], v[66:67], v[40:41] op_sel_hi:[0,1]
	v_pk_mul_f32 v[42:43], v[12:13], v[42:43]
	v_pk_mul_f32 v[40:41], v[14:15], v[40:41]
	v_bfe_u32 v44, v43, 16, 1
	v_bfe_u32 v45, v42, 16, 1
	v_add3_u32 v42, v42, v45, s84
	v_add3_u32 v43, v43, v44, s84
	v_bfe_u32 v44, v68, 16, 1
	v_bfe_u32 v45, v69, 16, 1
	v_bfe_u32 v53, v40, 16, 1
	v_bfe_u32 v58, v41, 16, 1
	v_bfe_u32 v46, v71, 16, 1
	v_bfe_u32 v47, v70, 16, 1
	v_add3_u32 v41, v41, v58, s84
	v_add3_u32 v40, v40, v53, s84
	v_add3_u32 v45, v69, v45, s84
	v_add3_u32 v44, v68, v44, s84
	v_add3_u32 v47, v70, v47, s84
	v_add3_u32 v46, v71, v46, s84
	v_lshrrev_b32_e32 v44, 16, v44
	v_lshrrev_b32_e32 v45, 16, v45
	v_lshrrev_b32_e32 v40, 16, v40
	v_lshrrev_b32_e32 v41, 16, v41
	v_and_or_b32 v43, v43, s3, v41
	v_and_or_b32 v42, v42, s3, v40
	v_and_or_b32 v41, v46, s3, v45
	v_and_or_b32 v40, v47, s3, v44
	global_store_dwordx4 v[56:57], v[40:43], off offset:16
	s_or_b64 exec, exec, s[36:37]
	s_and_saveexec_b64 s[36:37], vcc
	s_cbranch_execz .LBB0_169
; __device__ __forceinline__ u32x4 pack8(const float* f) { u32x4 o; o.x = pk2(f[0], f[1]); o.y = pk2(f[2], f[3]); o.z = pk2(f[4], f[5]); o.w = pk2(f[6], f[7]); return o; }
; __device__ __forceinline__ void phase_norm(bf16* Y, const float* g, int tid) {
;     ...
;         for (int u = 0; u < 4; ++u) { const int t = t0 + u * NGW; if (t < T) {
;             bf16* row = Y + (size_t)t * DM + lane * 16;
;             float y[16];
;             unpack8(ya[u][0], y); unpack8(ya[u][1], y + 8);
;             float ss = 0.f;
; #pragma unroll
;             for (int i = 0; i < 16; ++i) ss += y[i] * y[i];
;             ss += __shfl_xor(ss, 1); ss += __shfl_xor(ss, 2); ss += __shfl_xor(ss, 4); ss += __shfl_xor(ss, 8);
;             const float r = rsqrtf(ss * (1.f / 256.f) + 1e-6f);
; #pragma unroll
;             for (int i = 0; i < 16; ++i) y[i] = y[i] * r * gg[i];
;             *(u32x4*)row = pack8(y); *(u32x4*)(row + 8) = pack8(y + 8); } }
.LBB0_181:
	v_lshlrev_b32_e32 v57, 16, v25
	v_lshlrev_b32_e32 v56, 16, v24
	v_and_b32_e32 v59, 0xffff0000, v25
	v_and_b32_e32 v58, 0xffff0000, v24
	v_pk_mul_f32 v[64:65], v[56:57], v[56:57]
	v_pk_mul_f32 v[66:67], v[58:59], v[58:59]
	v_lshlrev_b32_e32 v69, 16, v27
	v_add_f32_e32 v53, v64, v66
	v_lshlrev_b32_e32 v68, 16, v26
	v_add_f32_e32 v53, v65, v53
	v_and_b32_e32 v71, 0xffff0000, v27
	v_and_b32_e32 v70, 0xffff0000, v26
	v_pk_mul_f32 v[72:73], v[68:69], v[68:69]
	v_add_f32_e32 v53, v67, v53
	v_pk_mul_f32 v[74:75], v[70:71], v[70:71]
	v_add_f32_e32 v53, v72, v53
	v_add_f32_e32 v53, v74, v53
	v_add_f32_e32 v53, v73, v53
	v_lshlrev_b32_e32 v77, 16, v17
	v_lshlrev_b32_e32 v76, 16, v16
	v_and_b32_e32 v79, 0xffff0000, v17
	v_add_f32_e32 v53, v75, v53
	v_and_b32_e32 v78, 0xffff0000, v16
	v_mov_b32_e32 v80, v79
	v_mov_b32_e32 v81, v77
	v_fmac_f32_e32 v53, v76, v76
	v_pk_mul_f32 v[80:81], v[80:81], v[80:81]
	v_fmac_f32_e32 v53, v78, v78
	v_and_b32_e32 v44, 0xffff0000, v18
	v_lshlrev_b32_e32 v45, 16, v18
	v_add_f32_e32 v53, v81, v53
	v_pk_mul_f32 v[40:41], v[44:45], v[44:45]
	v_add_f32_e32 v53, v80, v53
	v_and_b32_e32 v46, 0xffff0000, v19
	v_lshlrev_b32_e32 v47, 16, v19
	v_add_f32_e32 v41, v41, v53
	v_pk_mul_f32 v[42:43], v[46:47], v[46:47]
	v_add_f32_e32 v40, v40, v41
	v_add_f32_e32 v40, v43, v40
	v_add_f32_e32 v40, v42, v40
	s_waitcnt lgkmcnt(0)
	s_nop 1
	v_add_f32_dpp v40, v40, v40 quad_perm:[1,0,3,2] row_mask:0xf bank_mask:0xf
	s_waitcnt lgkmcnt(0)
	s_nop 1
	v_add_f32_dpp v40, v40, v40 quad_perm:[2,3,0,1] row_mask:0xf bank_mask:0xf
	s_waitcnt lgkmcnt(0)
	s_nop 1
	v_add_f32_dpp v40, v40, v40 row_half_mirror row_mask:0xf bank_mask:0xf
	s_waitcnt lgkmcnt(0)
	s_nop 1
	v_add_f32_dpp v40, v40, v40 row_mirror row_mask:0xf bank_mask:0xf
	v_fmamk_f32 v40, v40, 0x3b800000, v165
	v_mul_f32_e32 v41, 0x4b800000, v40
	v_cmp_gt_f32_e32 vcc, s9, v40
	s_nop 1
	v_cndmask_b32_e32 v40, v40, v41, vcc
	v_rsq_f32_e32 v42, v40
	v_lshlrev_b64 v[40:41], 11, v[54:55]
	v_lshl_add_u64 v[54:55], v[48:49], 0, v[40:41]
	v_mul_f32_e32 v40, 0x45800000, v42
	v_cndmask_b32_e32 v64, v42, v40, vcc
	v_pk_mul_f32 v[42:43], v[64:65], v[58:59] op_sel_hi:[0,1]
	v_pk_mul_f32 v[58:59], v[64:65], v[70:71] op_sel_hi:[0,1]
	v_pk_mul_f32 v[40:41], v[64:65], v[56:57] op_sel_hi:[0,1]
	v_pk_mul_f32 v[42:43], v[50:51], v[42:43]
	v_pk_mul_f32 v[56:57], v[64:65], v[68:69] op_sel_hi:[0,1]
	v_pk_mul_f32 v[58:59], v[4:5], v[58:59]
	v_pk_mul_f32 v[40:41], v[2:3], v[40:41]
	v_pk_mul_f32 v[56:57], v[6:7], v[56:57]
	v_pk_mul_f32 v[66:67], v[64:65], v[76:77] op_sel_hi:[0,1]
	v_pk_mul_f32 v[68:69], v[64:65], v[78:79] op_sel_hi:[0,1]
	v_bfe_u32 v53, v59, 16, 1
	v_bfe_u32 v63, v58, 16, 1
	v_bfe_u32 v65, v43, 16, 1
	v_bfe_u32 v70, v42, 16, 1
	v_add3_u32 v70, v42, v70, s84
	v_add3_u32 v65, v43, v65, s84
	v_add3_u32 v42, v58, v63, s84
	v_add3_u32 v43, v59, v53, s84
	v_bfe_u32 v53, v40, 16, 1
	v_bfe_u32 v58, v41, 16, 1
	v_bfe_u32 v59, v56, 16, 1
	v_bfe_u32 v63, v57, 16, 1
	v_add3_u32 v57, v57, v63, s84
	v_add3_u32 v56, v56, v59, s84
	v_add3_u32 v41, v41, v58, s84
	v_add3_u32 v40, v40, v53, s84
	v_lshrrev_b32_e32 v40, 16, v40
	v_lshrrev_b32_e32 v41, 16, v41
	v_lshrrev_b32_e32 v53, 16, v56
	v_lshrrev_b32_e32 v56, 16, v57
	v_and_or_b32 v43, v43, s3, v56
	v_and_or_b32 v42, v42, s3, v53
	v_and_or_b32 v41, v65, s3, v41
	v_and_or_b32 v40, v70, s3, v40
	global_store_dwordx4 v[54:55], v[40:43], off
	v_pk_mul_f32 v[66:67], v[10:11], v[66:67]
	v_pk_mul_f32 v[68:69], v[8:9], v[68:69]
	v_mov_b32_e32 v40, v45
	v_mov_b32_e32 v45, v46
	v_mov_b32_e32 v41, v47
	v_pk_mul_f32 v[42:43], v[64:65], v[44:45] op_sel_hi:[0,1]
	v_pk_mul_f32 v[40:41], v[64:65], v[40:41] op_sel_hi:[0,1]
	v_pk_mul_f32 v[42:43], v[12:13], v[42:43]
	v_pk_mul_f32 v[40:41], v[14:15], v[40:41]
	v_bfe_u32 v44, v43, 16, 1
	v_bfe_u32 v45, v42, 16, 1
	v_add3_u32 v42, v42, v45, s84
	v_add3_u32 v43, v43, v44, s84
	v_bfe_u32 v44, v66, 16, 1
	v_bfe_u32 v45, v67, 16, 1
	v_bfe_u32 v53, v40, 16, 1
	v_bfe_u32 v56, v41, 16, 1
	v_bfe_u32 v46, v69, 16, 1
	v_bfe_u32 v47, v68, 16, 1
	v_add3_u32 v41, v41, v56, s84
	v_add3_u32 v40, v40, v53, s84
	v_add3_u32 v45, v67, v45, s84
	v_add3_u32 v44, v66, v44, s84
	v_add3_u32 v47, v68, v47, s84
	v_add3_u32 v46, v69, v46, s84
	v_lshrrev_b32_e32 v44, 16, v44
	v_lshrrev_b32_e32 v45, 16, v45
	v_lshrrev_b32_e32 v40, 16, v40
	v_lshrrev_b32_e32 v41, 16, v41
	v_and_or_b32 v43, v43, s3, v41
	v_and_or_b32 v42, v42, s3, v40
	v_and_or_b32 v41, v46, s3, v45
	v_and_or_b32 v40, v47, s3, v44
	global_store_dwordx4 v[54:55], v[40:43], off offset:16
	s_branch .LBB0_169
